# first K-iteration of each of the four GEMM loops peeled: accumulators start from inline 0 (128 v_mov zeroing per tile removed); attention ticket prefetched one unit ahead
# speedup vs baseline: 1.0181x; 1.0046x over previous
.LBB0_165:
	s_ashr_i32 s35, s34, 31
	s_lshl_b64 s[36:37], s[34:35], 19
	s_add_u32 s58, s40, s36
	s_addc_u32 s59, s41, s37
	s_and_b64 s[36:37], s[0:1], exec
	s_cselect_b32 s5, s59, s69
	s_cselect_b32 s33, s58, s68
	s_ashr_i32 s31, s30, 31
	s_lshl_b64 s[36:37], s[30:31], 19
	s_add_u32 s60, s55, s36
	s_addc_u32 s61, s88, s37
	s_and_b64 s[36:37], s[0:1], exec
	s_cselect_b32 s31, s61, s71
	s_cselect_b32 s35, s60, s70
	s_add_u32 s68, s68, 0x40080
	s_addc_u32 s69, s69, 0
	s_add_u32 s36, s70, 0x100
	s_addc_u32 s37, s71, 0
	s_mov_b32 s38, -2
	ds_read_b128 v[130:133], v210
	ds_read_b128 v[134:137], v210 offset:1024
	ds_read_b128 v[138:141], v210 offset:2048
	ds_read_b128 v[142:145], v210 offset:3072
	ds_read_b128 v[146:149], v211
	ds_read_b128 v[150:153], v211 offset:1024
	ds_read_b128 v[154:157], v211 offset:2048
	ds_read_b128 v[158:161], v211 offset:3072
	s_add_u32 s39, s68, 0xfffc0080
	s_addc_u32 s42, s69, -1
	s_cmp_eq_u32 s38, 12
	s_cselect_b32 s73, s5, s42
	s_cselect_b32 s72, s33, s39
	s_cselect_b32 s71, s31, s37
	s_cselect_b32 s70, s35, s36
	v_lshl_add_u64 v[202:203], s[68:69], 0, v[186:187]
	s_add_i32 m0, s93, 0xc000
	ds_read_b128 v[194:197], v212
	ds_read_b128 v[198:201], v212 offset:1024
	ds_read_b128 v[214:217], v212 offset:2048
	ds_read_b128 v[218:221], v212 offset:3072
	ds_read_b128 v[222:225], v212 offset:4096
	ds_read_b128 v[226:229], v212 offset:5120
	ds_read_b128 v[230:233], v212 offset:6144
	ds_read_b128 v[234:237], v212 offset:7168
	global_load_lds_dwordx4 v[202:203], off
	v_lshl_add_u64 v[202:203], s[68:69], 0, v[188:189]
	s_add_i32 m0, s93, 0xe000
	s_nop 0
	global_load_lds_dwordx4 v[202:203], off
	s_waitcnt vmcnt(8)
	s_waitcnt lgkmcnt(0)
	s_barrier
	s_setprio 1
	s_waitcnt lgkmcnt(0)
	v_mfma_f32_16x16x32_bf16 v[126:129], v[130:133], v[194:197], 0
	v_mfma_f32_16x16x32_bf16 v[122:125], v[138:141], v[194:197], 0
	v_mfma_f32_16x16x32_bf16 v[110:113], v[130:133], v[214:217], 0
	v_mfma_f32_16x16x32_bf16 v[106:109], v[138:141], v[214:217], 0
	v_mfma_f32_16x16x32_bf16 v[94:97], v[130:133], v[222:225], 0
	v_mfma_f32_16x16x32_bf16 v[90:93], v[138:141], v[222:225], 0
	v_mfma_f32_16x16x32_bf16 v[78:81], v[130:133], v[230:233], 0
	v_mfma_f32_16x16x32_bf16 v[74:77], v[138:141], v[230:233], 0
	v_mfma_f32_16x16x32_bf16 v[126:129], v[134:137], v[198:201], v[126:129]
	v_mfma_f32_16x16x32_bf16 v[122:125], v[142:145], v[198:201], v[122:125]
	v_mfma_f32_16x16x32_bf16 v[110:113], v[134:137], v[218:221], v[110:113]
	v_mfma_f32_16x16x32_bf16 v[106:109], v[142:145], v[218:221], v[106:109]
	v_mfma_f32_16x16x32_bf16 v[94:97], v[134:137], v[226:229], v[94:97]
	v_mfma_f32_16x16x32_bf16 v[90:93], v[142:145], v[226:229], v[90:93]
	v_mfma_f32_16x16x32_bf16 v[78:81], v[134:137], v[234:237], v[78:81]
	v_mfma_f32_16x16x32_bf16 v[74:77], v[142:145], v[234:237], v[74:77]
	s_setprio 0
	s_setprio 1
	v_mfma_f32_16x16x32_bf16 v[118:121], v[146:149], v[194:197], 0
	v_mfma_f32_16x16x32_bf16 v[114:117], v[154:157], v[194:197], 0
	v_mfma_f32_16x16x32_bf16 v[102:105], v[146:149], v[214:217], 0
	v_mfma_f32_16x16x32_bf16 v[98:101], v[154:157], v[214:217], 0
	v_mfma_f32_16x16x32_bf16 v[86:89], v[146:149], v[222:225], 0
	v_mfma_f32_16x16x32_bf16 v[82:85], v[154:157], v[222:225], 0
	v_mfma_f32_16x16x32_bf16 v[70:73], v[146:149], v[230:233], 0
	v_mfma_f32_16x16x32_bf16 v[66:69], v[154:157], v[230:233], 0
	v_mfma_f32_16x16x32_bf16 v[118:121], v[150:153], v[198:201], v[118:121]
	v_mfma_f32_16x16x32_bf16 v[114:117], v[158:161], v[198:201], v[114:117]
	v_mfma_f32_16x16x32_bf16 v[102:105], v[150:153], v[218:221], v[102:105]
	v_mfma_f32_16x16x32_bf16 v[98:101], v[158:161], v[218:221], v[98:101]
	v_mfma_f32_16x16x32_bf16 v[86:89], v[150:153], v[226:229], v[86:89]
	v_mfma_f32_16x16x32_bf16 v[82:85], v[158:161], v[226:229], v[82:85]
	v_mfma_f32_16x16x32_bf16 v[70:73], v[150:153], v[234:237], v[70:73]
	v_mfma_f32_16x16x32_bf16 v[66:69], v[158:161], v[234:237], v[66:69]
	s_setprio 0
	s_barrier
	s_add_i32 s39, s86, s89
	v_lshl_add_u64 v[202:203], s[70:71], 0, v[170:171]
	s_mov_b32 m0, s39
	ds_read_b128 v[194:197], v212 offset:16384
	ds_read_b128 v[198:201], v212 offset:17408
	ds_read_b128 v[214:217], v212 offset:18432
	ds_read_b128 v[218:221], v212 offset:19456
	ds_read_b128 v[222:225], v212 offset:20480
	ds_read_b128 v[226:229], v212 offset:21504
	ds_read_b128 v[230:233], v212 offset:22528
	ds_read_b128 v[234:237], v212 offset:23552
	global_load_lds_dwordx4 v[202:203], off
	s_add_i32 m0, s39, 0x2000
	s_add_u32 s42, s70, 0x40000
	v_lshl_add_u64 v[238:239], s[70:71], 0, v[174:175]
	s_addc_u32 s43, s71, 0
	s_add_i32 s39, s87, s89
	global_load_lds_dwordx4 v[238:239], off
	v_lshl_add_u64 v[240:241], s[42:43], 0, v[170:171]
	s_mov_b32 m0, s39
	v_lshl_add_u64 v[242:243], s[72:73], 0, v[172:173]
	global_load_lds_dwordx4 v[240:241], off
	v_lshl_add_u64 v[240:241], s[42:43], 0, v[174:175]
	s_add_i32 m0, s39, 0x2000
	s_nop 0
	global_load_lds_dwordx4 v[240:241], off
	v_lshl_add_u64 v[240:241], s[72:73], 0, v[168:169]
	s_mov_b32 m0, s93
	s_nop 0
	global_load_lds_dwordx4 v[240:241], off
	s_mov_b32 m0, s94
	s_nop 0
	global_load_lds_dwordx4 v[242:243], off
	s_waitcnt vmcnt(8)
	s_waitcnt lgkmcnt(0)
	s_barrier
	s_setprio 1
	s_waitcnt lgkmcnt(0)
	v_mfma_f32_16x16x32_bf16 v[62:65], v[130:133], v[194:197], 0
	v_mfma_f32_16x16x32_bf16 v[58:61], v[138:141], v[194:197], 0
	v_mfma_f32_16x16x32_bf16 v[46:49], v[130:133], v[214:217], 0
	v_mfma_f32_16x16x32_bf16 v[42:45], v[138:141], v[214:217], 0
	v_mfma_f32_16x16x32_bf16 v[30:33], v[130:133], v[222:225], 0
	v_mfma_f32_16x16x32_bf16 v[26:29], v[138:141], v[222:225], 0
	v_mfma_f32_16x16x32_bf16 v[14:17], v[130:133], v[230:233], 0
	v_mfma_f32_16x16x32_bf16 v[10:13], v[138:141], v[230:233], 0
	v_mfma_f32_16x16x32_bf16 v[62:65], v[134:137], v[198:201], v[62:65]
	v_mfma_f32_16x16x32_bf16 v[58:61], v[142:145], v[198:201], v[58:61]
	v_mfma_f32_16x16x32_bf16 v[46:49], v[134:137], v[218:221], v[46:49]
	v_mfma_f32_16x16x32_bf16 v[42:45], v[142:145], v[218:221], v[42:45]
	v_mfma_f32_16x16x32_bf16 v[30:33], v[134:137], v[226:229], v[30:33]
	v_mfma_f32_16x16x32_bf16 v[26:29], v[142:145], v[226:229], v[26:29]
	v_mfma_f32_16x16x32_bf16 v[14:17], v[134:137], v[234:237], v[14:17]
	v_mfma_f32_16x16x32_bf16 v[10:13], v[142:145], v[234:237], v[10:13]
	s_setprio 0
	s_setprio 1
	v_mfma_f32_16x16x32_bf16 v[54:57], v[146:149], v[194:197], 0
	v_mfma_f32_16x16x32_bf16 v[50:53], v[154:157], v[194:197], 0
	v_mfma_f32_16x16x32_bf16 v[38:41], v[146:149], v[214:217], 0
	v_mfma_f32_16x16x32_bf16 v[34:37], v[154:157], v[214:217], 0
	v_mfma_f32_16x16x32_bf16 v[22:25], v[146:149], v[222:225], 0
	v_mfma_f32_16x16x32_bf16 v[18:21], v[154:157], v[222:225], 0
	v_mfma_f32_16x16x32_bf16 v[6:9], v[146:149], v[230:233], 0
	v_mfma_f32_16x16x32_bf16 v[2:5], v[154:157], v[230:233], 0
	v_mfma_f32_16x16x32_bf16 v[54:57], v[150:153], v[198:201], v[54:57]
	v_mfma_f32_16x16x32_bf16 v[50:53], v[158:161], v[198:201], v[50:53]
	v_mfma_f32_16x16x32_bf16 v[38:41], v[150:153], v[218:221], v[38:41]
	v_mfma_f32_16x16x32_bf16 v[34:37], v[158:161], v[218:221], v[34:37]
	v_mfma_f32_16x16x32_bf16 v[22:25], v[150:153], v[226:229], v[22:25]
	v_mfma_f32_16x16x32_bf16 v[18:21], v[158:161], v[226:229], v[18:21]
	v_mfma_f32_16x16x32_bf16 v[6:9], v[150:153], v[234:237], v[6:9]
	v_mfma_f32_16x16x32_bf16 v[2:5], v[158:161], v[234:237], v[2:5]
	s_setprio 0
	s_barrier
	s_add_i32 s39, 0, 0x18000
	s_add_i32 s44, 0, 0x1c000
	v_add_u32_e32 v142, s39, v206
	v_add_u32_e32 v158, s44, v206
	ds_read_b128 v[130:133], v142
	ds_read_b128 v[134:137], v142 offset:1024
	ds_read_b128 v[138:141], v142 offset:2048
	ds_read_b128 v[142:145], v142 offset:3072
	ds_read_b128 v[146:149], v158
	ds_read_b128 v[150:153], v158 offset:1024
	ds_read_b128 v[154:157], v158 offset:2048
	ds_read_b128 v[158:161], v158 offset:3072
	s_add_u32 s42, s72, 0x40000
	s_addc_u32 s43, s73, 0
	s_mov_b32 m0, s95
	v_lshl_add_u64 v[244:245], s[42:43], 0, v[168:169]
	ds_read_b128 v[194:197], v212 offset:32768
	ds_read_b128 v[198:201], v212 offset:33792
	ds_read_b128 v[214:217], v212 offset:34816
	ds_read_b128 v[218:221], v212 offset:35840
	ds_read_b128 v[222:225], v212 offset:36864
	ds_read_b128 v[226:229], v212 offset:37888
	ds_read_b128 v[230:233], v212 offset:38912
	ds_read_b128 v[234:237], v212 offset:39936
	global_load_lds_dwordx4 v[244:245], off
	v_lshl_add_u64 v[244:245], s[42:43], 0, v[172:173]
	s_mov_b32 m0, s96
	s_nop 0
	global_load_lds_dwordx4 v[244:245], off
	s_waitcnt vmcnt(8)
	s_waitcnt lgkmcnt(0)
	s_barrier
	s_setprio 1
	s_waitcnt lgkmcnt(0)
	v_mfma_f32_16x16x32_bf16 v[126:129], v[130:133], v[194:197], v[126:129]
	v_mfma_f32_16x16x32_bf16 v[122:125], v[138:141], v[194:197], v[122:125]
	v_mfma_f32_16x16x32_bf16 v[110:113], v[130:133], v[214:217], v[110:113]
	v_mfma_f32_16x16x32_bf16 v[106:109], v[138:141], v[214:217], v[106:109]
	v_mfma_f32_16x16x32_bf16 v[94:97], v[130:133], v[222:225], v[94:97]
	v_mfma_f32_16x16x32_bf16 v[90:93], v[138:141], v[222:225], v[90:93]
	v_mfma_f32_16x16x32_bf16 v[78:81], v[130:133], v[230:233], v[78:81]
	v_mfma_f32_16x16x32_bf16 v[74:77], v[138:141], v[230:233], v[74:77]
	v_mfma_f32_16x16x32_bf16 v[126:129], v[134:137], v[198:201], v[126:129]
	v_mfma_f32_16x16x32_bf16 v[122:125], v[142:145], v[198:201], v[122:125]
	v_mfma_f32_16x16x32_bf16 v[110:113], v[134:137], v[218:221], v[110:113]
	v_mfma_f32_16x16x32_bf16 v[106:109], v[142:145], v[218:221], v[106:109]
	v_mfma_f32_16x16x32_bf16 v[94:97], v[134:137], v[226:229], v[94:97]
	v_mfma_f32_16x16x32_bf16 v[90:93], v[142:145], v[226:229], v[90:93]
	v_mfma_f32_16x16x32_bf16 v[78:81], v[134:137], v[234:237], v[78:81]
	v_mfma_f32_16x16x32_bf16 v[74:77], v[142:145], v[234:237], v[74:77]
	s_setprio 0
	s_setprio 1
	v_mfma_f32_16x16x32_bf16 v[118:121], v[146:149], v[194:197], v[118:121]
	v_mfma_f32_16x16x32_bf16 v[114:117], v[154:157], v[194:197], v[114:117]
	v_mfma_f32_16x16x32_bf16 v[102:105], v[146:149], v[214:217], v[102:105]
	v_mfma_f32_16x16x32_bf16 v[98:101], v[154:157], v[214:217], v[98:101]
	v_mfma_f32_16x16x32_bf16 v[86:89], v[146:149], v[222:225], v[86:89]
	v_mfma_f32_16x16x32_bf16 v[82:85], v[154:157], v[222:225], v[82:85]
	v_mfma_f32_16x16x32_bf16 v[70:73], v[146:149], v[230:233], v[70:73]
	v_mfma_f32_16x16x32_bf16 v[66:69], v[154:157], v[230:233], v[66:69]
	v_mfma_f32_16x16x32_bf16 v[118:121], v[150:153], v[198:201], v[118:121]
	v_mfma_f32_16x16x32_bf16 v[114:117], v[158:161], v[198:201], v[114:117]
	v_mfma_f32_16x16x32_bf16 v[102:105], v[150:153], v[218:221], v[102:105]
	v_mfma_f32_16x16x32_bf16 v[98:101], v[158:161], v[218:221], v[98:101]
	v_mfma_f32_16x16x32_bf16 v[86:89], v[150:153], v[226:229], v[86:89]
	v_mfma_f32_16x16x32_bf16 v[82:85], v[158:161], v[226:229], v[82:85]
	v_mfma_f32_16x16x32_bf16 v[70:73], v[150:153], v[234:237], v[70:73]
	v_mfma_f32_16x16x32_bf16 v[66:69], v[158:161], v[234:237], v[66:69]
	s_setprio 0
	s_barrier
	s_add_i32 s39, s39, s89
	v_lshl_add_u64 v[202:203], v[202:203], 0, s[14:15]
	s_mov_b32 m0, s39
	ds_read_b128 v[194:197], v212 offset:49152
	ds_read_b128 v[198:201], v212 offset:50176
	ds_read_b128 v[214:217], v212 offset:51200
	ds_read_b128 v[218:221], v212 offset:52224
	ds_read_b128 v[222:225], v212 offset:53248
	ds_read_b128 v[226:229], v212 offset:54272
	ds_read_b128 v[230:233], v212 offset:55296
	ds_read_b128 v[234:237], v212 offset:56320
	global_load_lds_dwordx4 v[202:203], off
	s_add_i32 m0, s39, 0x2000
	s_add_u32 s42, s70, 0x40080
	v_lshl_add_u64 v[202:203], v[238:239], 0, s[14:15]
	s_addc_u32 s43, s71, 0
	s_add_i32 s39, s44, s89
	global_load_lds_dwordx4 v[202:203], off
	v_lshl_add_u64 v[202:203], s[42:43], 0, v[170:171]
	s_mov_b32 m0, s39
	s_nop 0
	global_load_lds_dwordx4 v[202:203], off
	v_lshl_add_u64 v[202:203], s[42:43], 0, v[174:175]
	s_add_i32 m0, s39, 0x2000
	s_nop 0
	global_load_lds_dwordx4 v[202:203], off
	v_lshl_add_u64 v[202:203], v[240:241], 0, s[14:15]
	s_mov_b32 m0, s85
	s_nop 0
	global_load_lds_dwordx4 v[202:203], off
	v_lshl_add_u64 v[202:203], v[242:243], 0, s[14:15]
	s_mov_b32 m0, s3
	s_nop 0
	global_load_lds_dwordx4 v[202:203], off
	s_waitcnt vmcnt(8)
	s_waitcnt lgkmcnt(0)
	s_barrier
	s_setprio 1
	s_waitcnt lgkmcnt(0)
	v_mfma_f32_16x16x32_bf16 v[62:65], v[130:133], v[194:197], v[62:65]
	v_mfma_f32_16x16x32_bf16 v[58:61], v[138:141], v[194:197], v[58:61]
	v_mfma_f32_16x16x32_bf16 v[46:49], v[130:133], v[214:217], v[46:49]
	v_mfma_f32_16x16x32_bf16 v[42:45], v[138:141], v[214:217], v[42:45]
	v_mfma_f32_16x16x32_bf16 v[30:33], v[130:133], v[222:225], v[30:33]
	v_mfma_f32_16x16x32_bf16 v[26:29], v[138:141], v[222:225], v[26:29]
	v_mfma_f32_16x16x32_bf16 v[14:17], v[130:133], v[230:233], v[14:17]
	v_mfma_f32_16x16x32_bf16 v[10:13], v[138:141], v[230:233], v[10:13]
	v_mfma_f32_16x16x32_bf16 v[62:65], v[134:137], v[198:201], v[62:65]
	v_mfma_f32_16x16x32_bf16 v[58:61], v[142:145], v[198:201], v[58:61]
	v_mfma_f32_16x16x32_bf16 v[46:49], v[134:137], v[218:221], v[46:49]
	v_mfma_f32_16x16x32_bf16 v[42:45], v[142:145], v[218:221], v[42:45]
	v_mfma_f32_16x16x32_bf16 v[30:33], v[134:137], v[226:229], v[30:33]
	v_mfma_f32_16x16x32_bf16 v[26:29], v[142:145], v[226:229], v[26:29]
	v_mfma_f32_16x16x32_bf16 v[14:17], v[134:137], v[234:237], v[14:17]
	v_mfma_f32_16x16x32_bf16 v[10:13], v[142:145], v[234:237], v[10:13]
	s_setprio 0
	s_setprio 1
	v_mfma_f32_16x16x32_bf16 v[54:57], v[146:149], v[194:197], v[54:57]
	v_mfma_f32_16x16x32_bf16 v[50:53], v[154:157], v[194:197], v[50:53]
	v_mfma_f32_16x16x32_bf16 v[38:41], v[146:149], v[214:217], v[38:41]
	v_mfma_f32_16x16x32_bf16 v[34:37], v[154:157], v[214:217], v[34:37]
	v_mfma_f32_16x16x32_bf16 v[22:25], v[146:149], v[222:225], v[22:25]
	v_mfma_f32_16x16x32_bf16 v[18:21], v[154:157], v[222:225], v[18:21]
	v_mfma_f32_16x16x32_bf16 v[6:9], v[146:149], v[230:233], v[6:9]
	v_mfma_f32_16x16x32_bf16 v[2:5], v[154:157], v[230:233], v[2:5]
	v_mfma_f32_16x16x32_bf16 v[54:57], v[150:153], v[198:201], v[54:57]
	v_mfma_f32_16x16x32_bf16 v[50:53], v[158:161], v[198:201], v[50:53]
	v_mfma_f32_16x16x32_bf16 v[38:41], v[150:153], v[218:221], v[38:41]
	v_mfma_f32_16x16x32_bf16 v[34:37], v[158:161], v[218:221], v[34:37]
	v_mfma_f32_16x16x32_bf16 v[22:25], v[150:153], v[226:229], v[22:25]
	v_mfma_f32_16x16x32_bf16 v[18:21], v[158:161], v[226:229], v[18:21]
	v_mfma_f32_16x16x32_bf16 v[6:9], v[150:153], v[234:237], v[6:9]
	v_mfma_f32_16x16x32_bf16 v[2:5], v[158:161], v[234:237], v[2:5]
	s_setprio 0
	s_barrier
	s_add_i32 s38, s38, 2
	s_add_u32 s68, s68, 0x100
	s_addc_u32 s69, s69, 0
	s_add_u32 s36, s36, 0x100
	s_addc_u32 s37, s37, 0

.LBB0_385:
	s_movk_i32 s0, 0x100
	v_cmp_gt_u32_e64 s[34:35], s0, v0
	s_movk_i32 s0, 0xff
	v_cmp_lt_u32_e64 s[72:73], s0, v0
	s_movk_i32 s0, 0x300
	v_lshrrev_b32_e32 v6, 2, v0
	v_cmp_gt_u32_e64 s[84:85], s0, v0
	s_movk_i32 s0, 0x2ff
	v_and_b32_e32 v165, 8, v6
	v_lshrrev_b32_e32 v173, 4, v170
	v_cmp_lt_u32_e64 s[88:89], s0, v0
	v_or_b32_e32 v6, 0xc00, v0
	s_movk_i32 s0, 0xd00
	v_lshlrev_b32_e32 v170, 4, v0
	v_bfe_u32 v3, v0, 4, 2
	v_lshrrev_b32_e32 v179, 4, v6
	v_cmp_gt_u32_e64 s[94:95], s0, v6
	v_and_b32_e32 v6, 0xf0, v170
	v_and_b32_e32 v9, 62, v163
	v_add_u32_e32 v163, 0, v6
	v_add_u32_e32 v187, 0, v2
	v_lshlrev_b32_e32 v6, 2, v3
	v_and_b32_e32 v2, 16, v0
	v_or_b32_e32 v8, 64, v160
	s_movk_i32 s55, 0x1d8
	v_readlane_b32 s16, v252, 1
	v_lshlrev_b32_e32 v5, 6, v185
	v_mov_b32_e32 v91, 0
	v_or_b32_e32 v180, 0xc0, v1
	s_movk_i32 s0, 0xd0
	v_mad_u32_u24 v191, v8, s55, 0
	v_add_u32_e32 v8, 12, v6
	v_cmp_eq_u32_e32 vcc, 0, v2
	v_lshlrev_b32_e32 v90, 5, v160
	v_readlane_b32 s24, v252, 9
	v_readlane_b32 s25, v252, 10
	v_lshrrev_b32_e32 v168, 4, v168
	v_lshrrev_b32_e32 v177, 4, v177
	v_cmp_gt_u32_e64 s[56:57], s0, v180
	s_movk_i32 s0, 0x110
	v_or_b32_e32 v11, v6, v5
	v_cndmask_b32_e32 v8, v8, v6, vcc
	v_add_u32_e32 v10, 44, v6
	v_or_b32_e32 v6, 32, v6
	v_lshl_add_u64 v[92:93], s[24:25], 0, v[90:91]
	v_lshlrev_b32_e32 v90, 4, v3
	v_lshlrev_b32_e32 v164, 3, v3
	v_mul_lo_u32 v182, v168, s0
	v_mul_lo_u32 v183, v173, s0
	v_mul_lo_u32 v184, v177, s0
	v_mad_u32_u24 v189, v160, s55, 0
	s_mov_b32 s0, 0xdd00
	v_cndmask_b32_e32 v10, v10, v6, vcc
	v_lshl_add_u64 v[12:13], s[80:81], 0, v[90:91]
	v_lshlrev_b32_e32 v90, 4, v160
	v_or_b32_e32 v7, 0x100, v5
	v_add3_u32 v190, v189, v164, s0
	v_or_b32_e32 v2, v8, v5
	v_or_b32_e32 v6, v10, v5
	v_or_b32_e32 v5, 0x800, v0
	s_movk_i32 s0, 0x8ff
	v_lshl_add_u64 v[94:95], s[48:49], 0, v[90:91]
	v_lshlrev_b32_e32 v90, 2, v185
	v_cmp_lt_u32_e64 s[42:43], s0, v5
	s_movk_i32 s0, 0xb00
	v_lshl_add_u64 v[96:97], s[64:65], 0, v[90:91]
	v_lshlrev_b32_e32 v90, 2, v11
	v_or_b32_e32 v178, 0xa0, v1
	v_cmp_gt_u32_e64 s[4:5], s0, v5
	s_movk_i32 s0, 0xb0
	v_lshl_add_u64 v[98:99], s[66:67], 0, v[90:91]
	v_lshlrev_b32_e32 v90, 7, v185
	v_cmp_gt_u32_e64 s[70:71], s0, v178
	v_readlane_b32 s20, v252, 5
	v_readlane_b32 s21, v252, 6
	v_lshl_add_u64 v[12:13], v[12:13], 0, v[90:91]
	s_mov_b64 s[0:1], 0x1dc88800
	v_lshlrev_b32_e32 v90, 1, v2
	v_lshl_add_u64 v[100:101], v[12:13], 0, s[0:1]
	v_lshl_add_u64 v[12:13], s[80:81], 0, v[90:91]
	s_mov_b64 s[20:21], 0x23d48c00
	v_lshl_add_u64 v[104:105], v[12:13], 0, s[20:21]
	v_lshlrev_b32_e32 v12, 1, v6
	v_mov_b32_e32 v13, v91
	v_lshl_add_u64 v[14:15], s[80:81], 0, v[12:13]
	v_or_b32_e32 v90, 0x200, v90
	v_lshrrev_b32_e32 v194, 4, v5
	v_lshl_add_u64 v[106:107], v[14:15], 0, s[20:21]
	v_lshl_add_u64 v[14:15], s[80:81], 0, v[90:91]
	v_or_b32_e32 v90, 0x200, v12
	v_lshrrev_b32_e32 v103, 4, v0
	v_lshrrev_b32_e32 v162, 2, v160
	v_lshlrev_b32_e32 v4, 3, v160
	v_or_b32_e32 v176, 0x80, v1
	v_or_b32_e32 v8, v8, v7
	v_or_b32_e32 v10, v10, v7
	s_movk_i32 s59, 0x8f
	v_mul_u32_u24_e32 v5, 0x110, v194
	v_readlane_b32 s22, v252, 7
	v_readlane_b32 s23, v252, 8
	v_lshl_add_u64 v[12:13], s[80:81], 0, v[90:91]
	v_or_b32_e32 v166, 0x10100, v1
	v_or_b32_e32 v167, 0x10100, v103
	v_cmp_gt_u32_e64 s[74:75], 16, v1
	v_or_b32_e32 v169, 32, v1
	v_or_b32_e32 v171, 64, v103
	v_or_b32_e32 v172, 64, v1
	v_or_b32_e32 v174, 0x60, v1
	v_or_b32_e32 v175, 0x80, v103
	v_mul_u32_u24_e32 v181, 0x110, v103
	v_mul_u32_u24_e32 v186, 0x110, v179
	v_mul_u32_u24_e32 v188, 0x110, v160
	v_lshlrev_b32_e32 v192, 7, v1
	v_lshlrev_b32_e32 v193, 7, v103
	v_cmp_lt_u32_e64 s[68:69], s59, v176
	v_or_b32_e32 v195, 0x10000, v162
	s_mov_b64 s[22:23], s[4:5]
	v_add_u32_e32 v102, 0, v9
	v_lshl_add_u64 v[108:109], v[14:15], 0, s[20:21]
	v_lshl_add_u64 v[110:111], v[12:13], 0, s[20:21]
	s_add_i32 s62, 0, 0x23fc0
	s_movk_i32 s63, 0x407
	s_movk_i32 s64, 0x1e00
	s_mov_b32 s58, 0xf149f2ca
	s_mov_b32 s65, 0x3fb8aa3b
	v_mov_b32_e32 v185, 0x358637bd
	s_mov_b32 s66, 0x800000
	v_lshlrev_b32_e32 v112, 2, v4
	v_add_u32_e32 v196, v163, v5
	v_lshlrev_b32_e32 v114, 1, v2
	v_lshlrev_b32_e32 v116, 1, v6
	v_lshlrev_b32_e32 v118, 1, v8
	v_lshlrev_b32_e32 v120, 1, v10
	s_waitcnt vmcnt(12)
	v_mbcnt_hi_u32_b32 v211, -1, v204
	v_mov_b32_e32 v197, 0xf149f2ca
	v_mov_b32_e32 v198, v91
	v_mov_b32_e32 v199, v91
	v_mov_b32_e32 v200, v91
	v_mov_b32_e32 v201, v91
	v_readlane_b32 s17, v252, 2
	v_readlane_b32 s18, v252, 3
	v_readlane_b32 s19, v252, 4
	v_readlane_b32 s26, v252, 11
	v_readlane_b32 s27, v252, 12
	v_readlane_b32 s28, v252, 13
	v_readlane_b32 s29, v252, 14
	v_readlane_b32 s30, v252, 15
	v_readlane_b32 s31, v252, 16
	global_load_dwordx4 v[224:227], v[98:99], off offset:64
	global_load_dwordx4 v[228:231], v[98:99], off offset:128
	global_load_dwordx4 v[232:235], v[98:99], off offset:192
	global_load_dwordx4 v[236:239], v[98:99], off offset:1024
	global_load_dwordx4 v[240:243], v[98:99], off offset:1088
	global_load_dwordx4 v[244:247], v[98:99], off offset:1152
	global_load_dwordx4 v[248:251], v[98:99], off offset:1216
	s_and_saveexec_b64 s[0:1], s[96:97]
	s_cbranch_execz .Lattn_tk0_done
	v_mov_b32_e32 v254, 1
	s_nop 0
	global_atomic_add v253, v91, v254, s[80:81] sc0
.Lattn_tk0_done:
	s_or_b64 exec, exec, s[0:1]
	s_branch .LBB0_389

.LBB0_389:
	s_barrier
	s_and_saveexec_b64 s[0:1], s[96:97]
	s_cbranch_execz .LBB0_393
	s_waitcnt vmcnt(0)
	v_mov_b32_e32 v255, v253
	v_mov_b32_e32 v3, s62
	v_mov_b32_e32 v254, 1
	ds_write_b32 v3, v255
	global_atomic_add v253, v91, v254, s[80:81] sc0

.LBB0_514:
	s_ashr_i32 s21, s20, 31
	s_lshl_b64 s[22:23], s[20:21], 19
	s_add_u32 s22, s10, s22
	s_addc_u32 s23, s11, s23
	s_and_b64 s[24:25], s[6:7], exec
	s_cselect_b32 s21, s23, s31
	s_cselect_b32 s27, s22, s30
	s_ashr_i32 s19, s18, 31
	s_lshl_b64 s[24:25], s[18:19], 19
	s_add_u32 s24, s3, s24
	s_addc_u32 s25, s46, s25
	s_and_b64 s[36:37], s[6:7], exec
	s_cselect_b32 s19, s25, s39
	s_cselect_b32 s33, s24, s38
	s_add_u32 s30, s30, 0x40080
	s_addc_u32 s31, s31, 0
	s_add_u32 s36, s38, 0x100
	s_addc_u32 s37, s39, 0
	s_mov_b32 s54, -2
	s_waitcnt lgkmcnt(0)
	s_waitcnt vmcnt(0)
	ds_read_b128 v[82:85], v193
	ds_read_b128 v[86:89], v193 offset:1024
	ds_read_b128 v[98:101], v193 offset:2048
	ds_read_b128 v[102:105], v193 offset:3072
	ds_read_b128 v[146:149], v195
	ds_read_b128 v[150:153], v195 offset:1024
	ds_read_b128 v[154:157], v195 offset:2048
	ds_read_b128 v[158:161], v195 offset:3072
	s_add_u32 s38, s30, 0xfffc0080
	s_addc_u32 s39, s31, -1
	s_cmp_eq_u32 s54, 12
	s_cselect_b32 s45, s21, s39
	s_cselect_b32 s44, s27, s38
	s_cselect_b32 s39, s19, s37
	s_cselect_b32 s38, s33, s36
	v_lshl_add_u64 v[190:191], s[30:31], 0, v[180:181]
	s_add_i32 m0, s29, 0xc000
	ds_read_b128 v[162:165], v197
	ds_read_b128 v[166:169], v197 offset:1024
	ds_read_b128 v[198:201], v197 offset:2048
	ds_read_b128 v[202:205], v197 offset:3072
	ds_read_b128 v[206:209], v197 offset:4096
	ds_read_b128 v[212:215], v197 offset:5120
	ds_read_b128 v[216:219], v197 offset:6144
	ds_read_b128 v[220:223], v197 offset:7168
	global_load_lds_dwordx4 v[190:191], off
	v_lshl_add_u64 v[190:191], s[30:31], 0, v[182:183]
	s_add_i32 m0, s29, 0xe000
	s_nop 0
	global_load_lds_dwordx4 v[190:191], off
	s_waitcnt vmcnt(8)
	s_waitcnt lgkmcnt(0)
	s_barrier
	s_setprio 1
	s_waitcnt lgkmcnt(0)
	v_mfma_f32_16x16x32_bf16 v[142:145], v[82:85], v[162:165], 0
	v_mfma_f32_16x16x32_bf16 v[138:141], v[98:101], v[162:165], 0
	v_mfma_f32_16x16x32_bf16 v[126:129], v[82:85], v[198:201], 0
	v_mfma_f32_16x16x32_bf16 v[122:125], v[98:101], v[198:201], 0
	v_mfma_f32_16x16x32_bf16 v[110:113], v[82:85], v[206:209], 0
	v_mfma_f32_16x16x32_bf16 v[106:109], v[98:101], v[206:209], 0
	v_mfma_f32_16x16x32_bf16 v[78:81], v[82:85], v[216:219], 0
	v_mfma_f32_16x16x32_bf16 v[74:77], v[98:101], v[216:219], 0
	v_mfma_f32_16x16x32_bf16 v[142:145], v[86:89], v[166:169], v[142:145]
	v_mfma_f32_16x16x32_bf16 v[138:141], v[102:105], v[166:169], v[138:141]
	v_mfma_f32_16x16x32_bf16 v[126:129], v[86:89], v[202:205], v[126:129]
	v_mfma_f32_16x16x32_bf16 v[122:125], v[102:105], v[202:205], v[122:125]
	v_mfma_f32_16x16x32_bf16 v[110:113], v[86:89], v[212:215], v[110:113]
	v_mfma_f32_16x16x32_bf16 v[106:109], v[102:105], v[212:215], v[106:109]
	v_mfma_f32_16x16x32_bf16 v[78:81], v[86:89], v[220:223], v[78:81]
	v_mfma_f32_16x16x32_bf16 v[74:77], v[102:105], v[220:223], v[74:77]
	s_setprio 0
	s_setprio 1
	v_mfma_f32_16x16x32_bf16 v[134:137], v[146:149], v[162:165], 0
	v_mfma_f32_16x16x32_bf16 v[130:133], v[154:157], v[162:165], 0
	v_mfma_f32_16x16x32_bf16 v[118:121], v[146:149], v[198:201], 0
	v_mfma_f32_16x16x32_bf16 v[114:117], v[154:157], v[198:201], 0
	v_mfma_f32_16x16x32_bf16 v[94:97], v[146:149], v[206:209], 0
	v_mfma_f32_16x16x32_bf16 v[90:93], v[154:157], v[206:209], 0
	v_mfma_f32_16x16x32_bf16 v[70:73], v[146:149], v[216:219], 0
	v_mfma_f32_16x16x32_bf16 v[66:69], v[154:157], v[216:219], 0
	v_mfma_f32_16x16x32_bf16 v[134:137], v[150:153], v[166:169], v[134:137]
	v_mfma_f32_16x16x32_bf16 v[130:133], v[158:161], v[166:169], v[130:133]
	v_mfma_f32_16x16x32_bf16 v[118:121], v[150:153], v[202:205], v[118:121]
	v_mfma_f32_16x16x32_bf16 v[114:117], v[158:161], v[202:205], v[114:117]
	v_mfma_f32_16x16x32_bf16 v[94:97], v[150:153], v[212:215], v[94:97]
	v_mfma_f32_16x16x32_bf16 v[90:93], v[158:161], v[212:215], v[90:93]
	v_mfma_f32_16x16x32_bf16 v[70:73], v[150:153], v[220:223], v[70:73]
	v_mfma_f32_16x16x32_bf16 v[66:69], v[158:161], v[220:223], v[66:69]
	s_setprio 0
	s_barrier
	s_add_i32 s42, s55, s47
	v_lshl_add_u64 v[190:191], s[38:39], 0, v[174:175]
	s_mov_b32 m0, s42
	ds_read_b128 v[162:165], v197 offset:16384
	ds_read_b128 v[166:169], v197 offset:17408
	ds_read_b128 v[198:201], v197 offset:18432
	ds_read_b128 v[202:205], v197 offset:19456
	ds_read_b128 v[206:209], v197 offset:20480
	ds_read_b128 v[212:215], v197 offset:21504
	ds_read_b128 v[216:219], v197 offset:22528
	ds_read_b128 v[220:223], v197 offset:23552
	global_load_lds_dwordx4 v[190:191], off
	s_add_i32 m0, s42, 0x2000
	s_add_u32 s42, s38, 0x40000
	v_lshl_add_u64 v[224:225], s[38:39], 0, v[178:179]
	s_addc_u32 s43, s39, 0
	s_add_i32 s57, s56, s47
	global_load_lds_dwordx4 v[224:225], off
	v_lshl_add_u64 v[226:227], s[42:43], 0, v[174:175]
	s_mov_b32 m0, s57
	v_lshl_add_u64 v[228:229], s[44:45], 0, v[176:177]
	global_load_lds_dwordx4 v[226:227], off
	v_lshl_add_u64 v[226:227], s[42:43], 0, v[178:179]
	s_add_i32 m0, s57, 0x2000
	s_nop 0
	global_load_lds_dwordx4 v[226:227], off
	v_lshl_add_u64 v[226:227], s[44:45], 0, v[172:173]
	s_mov_b32 m0, s29
	s_nop 0
	global_load_lds_dwordx4 v[226:227], off
	s_mov_b32 m0, s48
	s_nop 0
	global_load_lds_dwordx4 v[228:229], off
	s_waitcnt vmcnt(8)
	s_waitcnt lgkmcnt(0)
	s_barrier
	s_setprio 1
	s_waitcnt lgkmcnt(0)
	v_mfma_f32_16x16x32_bf16 v[62:65], v[82:85], v[162:165], 0
	v_mfma_f32_16x16x32_bf16 v[58:61], v[98:101], v[162:165], 0
	v_mfma_f32_16x16x32_bf16 v[46:49], v[82:85], v[198:201], 0
	v_mfma_f32_16x16x32_bf16 v[42:45], v[98:101], v[198:201], 0
	v_mfma_f32_16x16x32_bf16 v[30:33], v[82:85], v[206:209], 0
	v_mfma_f32_16x16x32_bf16 v[26:29], v[98:101], v[206:209], 0
	v_mfma_f32_16x16x32_bf16 v[14:17], v[82:85], v[216:219], 0
	v_mfma_f32_16x16x32_bf16 v[10:13], v[98:101], v[216:219], 0
	v_mfma_f32_16x16x32_bf16 v[62:65], v[86:89], v[166:169], v[62:65]
	v_mfma_f32_16x16x32_bf16 v[58:61], v[102:105], v[166:169], v[58:61]
	v_mfma_f32_16x16x32_bf16 v[46:49], v[86:89], v[202:205], v[46:49]
	v_mfma_f32_16x16x32_bf16 v[42:45], v[102:105], v[202:205], v[42:45]
	v_mfma_f32_16x16x32_bf16 v[30:33], v[86:89], v[212:215], v[30:33]
	v_mfma_f32_16x16x32_bf16 v[26:29], v[102:105], v[212:215], v[26:29]
	v_mfma_f32_16x16x32_bf16 v[14:17], v[86:89], v[220:223], v[14:17]
	v_mfma_f32_16x16x32_bf16 v[10:13], v[102:105], v[220:223], v[10:13]
	s_setprio 0
	s_setprio 1
	v_mfma_f32_16x16x32_bf16 v[54:57], v[146:149], v[162:165], 0
	v_mfma_f32_16x16x32_bf16 v[50:53], v[154:157], v[162:165], 0
	v_mfma_f32_16x16x32_bf16 v[38:41], v[146:149], v[198:201], 0
	v_mfma_f32_16x16x32_bf16 v[34:37], v[154:157], v[198:201], 0
	v_mfma_f32_16x16x32_bf16 v[22:25], v[146:149], v[206:209], 0
	v_mfma_f32_16x16x32_bf16 v[18:21], v[154:157], v[206:209], 0
	v_mfma_f32_16x16x32_bf16 v[6:9], v[146:149], v[216:219], 0
	v_mfma_f32_16x16x32_bf16 v[2:5], v[154:157], v[216:219], 0
	v_mfma_f32_16x16x32_bf16 v[54:57], v[150:153], v[166:169], v[54:57]
	v_mfma_f32_16x16x32_bf16 v[50:53], v[158:161], v[166:169], v[50:53]
	v_mfma_f32_16x16x32_bf16 v[38:41], v[150:153], v[202:205], v[38:41]
	v_mfma_f32_16x16x32_bf16 v[34:37], v[158:161], v[202:205], v[34:37]
	v_mfma_f32_16x16x32_bf16 v[22:25], v[150:153], v[212:215], v[22:25]
	v_mfma_f32_16x16x32_bf16 v[18:21], v[158:161], v[212:215], v[18:21]
	v_mfma_f32_16x16x32_bf16 v[6:9], v[150:153], v[220:223], v[6:9]
	v_mfma_f32_16x16x32_bf16 v[2:5], v[158:161], v[220:223], v[2:5]
	s_setprio 0
	s_barrier
	s_add_i32 s57, 0, 0x18000
	s_add_i32 s58, 0, 0x1c000
	v_add_u32_e32 v102, s57, v171
	v_add_u32_e32 v158, s58, v171
	ds_read_b128 v[82:85], v102
	ds_read_b128 v[86:89], v102 offset:1024
	ds_read_b128 v[98:101], v102 offset:2048
	ds_read_b128 v[102:105], v102 offset:3072
	ds_read_b128 v[146:149], v158
	ds_read_b128 v[150:153], v158 offset:1024
	ds_read_b128 v[154:157], v158 offset:2048
	ds_read_b128 v[158:161], v158 offset:3072
	s_add_u32 s42, s44, 0x40000
	s_addc_u32 s43, s45, 0
	s_mov_b32 m0, s49
	v_lshl_add_u64 v[230:231], s[42:43], 0, v[172:173]
	ds_read_b128 v[162:165], v197 offset:32768
	ds_read_b128 v[166:169], v197 offset:33792
	ds_read_b128 v[198:201], v197 offset:34816
	ds_read_b128 v[202:205], v197 offset:35840
	ds_read_b128 v[206:209], v197 offset:36864
	ds_read_b128 v[212:215], v197 offset:37888
	ds_read_b128 v[216:219], v197 offset:38912
	ds_read_b128 v[220:223], v197 offset:39936
	global_load_lds_dwordx4 v[230:231], off
	v_lshl_add_u64 v[230:231], s[42:43], 0, v[176:177]
	s_mov_b32 m0, s50
	s_nop 0
	global_load_lds_dwordx4 v[230:231], off
	s_waitcnt vmcnt(8)
	s_waitcnt lgkmcnt(0)
	s_barrier
	s_setprio 1
	s_waitcnt lgkmcnt(0)
	v_mfma_f32_16x16x32_bf16 v[142:145], v[82:85], v[162:165], v[142:145]
	v_mfma_f32_16x16x32_bf16 v[138:141], v[98:101], v[162:165], v[138:141]
	v_mfma_f32_16x16x32_bf16 v[126:129], v[82:85], v[198:201], v[126:129]
	v_mfma_f32_16x16x32_bf16 v[122:125], v[98:101], v[198:201], v[122:125]
	v_mfma_f32_16x16x32_bf16 v[110:113], v[82:85], v[206:209], v[110:113]
	v_mfma_f32_16x16x32_bf16 v[106:109], v[98:101], v[206:209], v[106:109]
	v_mfma_f32_16x16x32_bf16 v[78:81], v[82:85], v[216:219], v[78:81]
	v_mfma_f32_16x16x32_bf16 v[74:77], v[98:101], v[216:219], v[74:77]
	v_mfma_f32_16x16x32_bf16 v[142:145], v[86:89], v[166:169], v[142:145]
	v_mfma_f32_16x16x32_bf16 v[138:141], v[102:105], v[166:169], v[138:141]
	v_mfma_f32_16x16x32_bf16 v[126:129], v[86:89], v[202:205], v[126:129]
	v_mfma_f32_16x16x32_bf16 v[122:125], v[102:105], v[202:205], v[122:125]
	v_mfma_f32_16x16x32_bf16 v[110:113], v[86:89], v[212:215], v[110:113]
	v_mfma_f32_16x16x32_bf16 v[106:109], v[102:105], v[212:215], v[106:109]
	v_mfma_f32_16x16x32_bf16 v[78:81], v[86:89], v[220:223], v[78:81]
	v_mfma_f32_16x16x32_bf16 v[74:77], v[102:105], v[220:223], v[74:77]
	s_setprio 0
	s_setprio 1
	v_mfma_f32_16x16x32_bf16 v[134:137], v[146:149], v[162:165], v[134:137]
	v_mfma_f32_16x16x32_bf16 v[130:133], v[154:157], v[162:165], v[130:133]
	v_mfma_f32_16x16x32_bf16 v[118:121], v[146:149], v[198:201], v[118:121]
	v_mfma_f32_16x16x32_bf16 v[114:117], v[154:157], v[198:201], v[114:117]
	v_mfma_f32_16x16x32_bf16 v[94:97], v[146:149], v[206:209], v[94:97]
	v_mfma_f32_16x16x32_bf16 v[90:93], v[154:157], v[206:209], v[90:93]
	v_mfma_f32_16x16x32_bf16 v[70:73], v[146:149], v[216:219], v[70:73]
	v_mfma_f32_16x16x32_bf16 v[66:69], v[154:157], v[216:219], v[66:69]
	v_mfma_f32_16x16x32_bf16 v[134:137], v[150:153], v[166:169], v[134:137]
	v_mfma_f32_16x16x32_bf16 v[130:133], v[158:161], v[166:169], v[130:133]
	v_mfma_f32_16x16x32_bf16 v[118:121], v[150:153], v[202:205], v[118:121]
	v_mfma_f32_16x16x32_bf16 v[114:117], v[158:161], v[202:205], v[114:117]
	v_mfma_f32_16x16x32_bf16 v[94:97], v[150:153], v[212:215], v[94:97]
	v_mfma_f32_16x16x32_bf16 v[90:93], v[158:161], v[212:215], v[90:93]
	v_mfma_f32_16x16x32_bf16 v[70:73], v[150:153], v[220:223], v[70:73]
	v_mfma_f32_16x16x32_bf16 v[66:69], v[158:161], v[220:223], v[66:69]
	s_setprio 0
	s_barrier
	s_add_i32 s42, s57, s47
	v_lshl_add_u64 v[190:191], v[190:191], 0, s[14:15]
	s_mov_b32 m0, s42
	ds_read_b128 v[162:165], v197 offset:49152
	ds_read_b128 v[166:169], v197 offset:50176
	ds_read_b128 v[198:201], v197 offset:51200
	ds_read_b128 v[202:205], v197 offset:52224
	ds_read_b128 v[206:209], v197 offset:53248
	ds_read_b128 v[212:215], v197 offset:54272
	ds_read_b128 v[216:219], v197 offset:55296
	ds_read_b128 v[220:223], v197 offset:56320
	global_load_lds_dwordx4 v[190:191], off
	s_add_i32 m0, s42, 0x2000
	s_add_u32 s38, s38, 0x40080
	v_lshl_add_u64 v[190:191], v[224:225], 0, s[14:15]
	s_addc_u32 s39, s39, 0
	s_add_i32 s42, s58, s47
	global_load_lds_dwordx4 v[190:191], off
	v_lshl_add_u64 v[190:191], s[38:39], 0, v[174:175]
	s_mov_b32 m0, s42
	s_nop 0
	global_load_lds_dwordx4 v[190:191], off
	v_lshl_add_u64 v[190:191], s[38:39], 0, v[178:179]
	s_add_i32 m0, s42, 0x2000
	s_nop 0
	global_load_lds_dwordx4 v[190:191], off
	v_lshl_add_u64 v[190:191], v[226:227], 0, s[14:15]
	s_mov_b32 m0, s52
	s_nop 0
	global_load_lds_dwordx4 v[190:191], off
	v_lshl_add_u64 v[190:191], v[228:229], 0, s[14:15]
	s_mov_b32 m0, s53
	s_nop 0
	global_load_lds_dwordx4 v[190:191], off
	s_waitcnt vmcnt(8)
	s_waitcnt lgkmcnt(0)
	s_barrier
	s_setprio 1
	s_waitcnt lgkmcnt(0)
	v_mfma_f32_16x16x32_bf16 v[62:65], v[82:85], v[162:165], v[62:65]
	v_mfma_f32_16x16x32_bf16 v[58:61], v[98:101], v[162:165], v[58:61]
	v_mfma_f32_16x16x32_bf16 v[46:49], v[82:85], v[198:201], v[46:49]
	v_mfma_f32_16x16x32_bf16 v[42:45], v[98:101], v[198:201], v[42:45]
	v_mfma_f32_16x16x32_bf16 v[30:33], v[82:85], v[206:209], v[30:33]
	v_mfma_f32_16x16x32_bf16 v[26:29], v[98:101], v[206:209], v[26:29]
	v_mfma_f32_16x16x32_bf16 v[14:17], v[82:85], v[216:219], v[14:17]
	v_mfma_f32_16x16x32_bf16 v[10:13], v[98:101], v[216:219], v[10:13]
	v_mfma_f32_16x16x32_bf16 v[62:65], v[86:89], v[166:169], v[62:65]
	v_mfma_f32_16x16x32_bf16 v[58:61], v[102:105], v[166:169], v[58:61]
	v_mfma_f32_16x16x32_bf16 v[46:49], v[86:89], v[202:205], v[46:49]
	v_mfma_f32_16x16x32_bf16 v[42:45], v[102:105], v[202:205], v[42:45]
	v_mfma_f32_16x16x32_bf16 v[30:33], v[86:89], v[212:215], v[30:33]
	v_mfma_f32_16x16x32_bf16 v[26:29], v[102:105], v[212:215], v[26:29]
	v_mfma_f32_16x16x32_bf16 v[14:17], v[86:89], v[220:223], v[14:17]
	v_mfma_f32_16x16x32_bf16 v[10:13], v[102:105], v[220:223], v[10:13]
	s_setprio 0
	s_setprio 1
	v_mfma_f32_16x16x32_bf16 v[54:57], v[146:149], v[162:165], v[54:57]
	v_mfma_f32_16x16x32_bf16 v[50:53], v[154:157], v[162:165], v[50:53]
	v_mfma_f32_16x16x32_bf16 v[38:41], v[146:149], v[198:201], v[38:41]
	v_mfma_f32_16x16x32_bf16 v[34:37], v[154:157], v[198:201], v[34:37]
	v_mfma_f32_16x16x32_bf16 v[22:25], v[146:149], v[206:209], v[22:25]
	v_mfma_f32_16x16x32_bf16 v[18:21], v[154:157], v[206:209], v[18:21]
	v_mfma_f32_16x16x32_bf16 v[6:9], v[146:149], v[216:219], v[6:9]
	v_mfma_f32_16x16x32_bf16 v[2:5], v[154:157], v[216:219], v[2:5]
	v_mfma_f32_16x16x32_bf16 v[54:57], v[150:153], v[166:169], v[54:57]
	v_mfma_f32_16x16x32_bf16 v[50:53], v[158:161], v[166:169], v[50:53]
	v_mfma_f32_16x16x32_bf16 v[38:41], v[150:153], v[202:205], v[38:41]
	v_mfma_f32_16x16x32_bf16 v[34:37], v[158:161], v[202:205], v[34:37]
	v_mfma_f32_16x16x32_bf16 v[22:25], v[150:153], v[212:215], v[22:25]
	v_mfma_f32_16x16x32_bf16 v[18:21], v[158:161], v[212:215], v[18:21]
	v_mfma_f32_16x16x32_bf16 v[6:9], v[150:153], v[220:223], v[6:9]
	v_mfma_f32_16x16x32_bf16 v[2:5], v[158:161], v[220:223], v[2:5]
	s_setprio 0
	s_barrier
	s_add_i32 s54, s54, 2
	s_add_u32 s30, s30, 0x100
	s_addc_u32 s31, s31, 0
	s_add_u32 s36, s36, 0x100
	s_addc_u32 s37, s37, 0

.LBB0_605:
	s_ashr_i32 s23, s22, 31
	s_lshl_b64 s[24:25], s[22:23], 19
	s_add_u32 s24, s40, s24
	s_addc_u32 s25, s41, s25
	s_and_b64 s[26:27], s[4:5], exec
	s_cselect_b32 s23, s25, s29
	s_cselect_b32 s52, s24, s28
	s_ashr_i32 s21, s20, 31
	s_lshl_b64 s[26:27], s[20:21], 19
	s_add_u32 s26, s3, s26
	s_addc_u32 s27, s17, s27
	s_and_b64 s[38:39], s[4:5], exec
	s_cselect_b32 s21, s27, s31
	s_cselect_b32 s53, s26, s30
	s_cselect_b32 s38, s22, s0
	v_lshl_add_u32 v248, s38, 8, v1
	s_add_u32 s28, s28, 0x40080
	s_addc_u32 s29, s29, 0
	s_add_u32 s54, s30, 0x100
	s_addc_u32 s55, s31, 0
	s_mov_b32 s56, -2
	ds_read_b128 v[146:149], v154
	ds_read_b128 v[158:161], v154 offset:1024
	ds_read_b128 v[162:165], v154 offset:2048
	ds_read_b128 v[166:169], v154 offset:3072
	ds_read_b128 v[172:175], v155
	ds_read_b128 v[176:179], v155 offset:1024
	ds_read_b128 v[180:183], v155 offset:2048
	ds_read_b128 v[184:187], v155 offset:3072
	s_add_u32 s30, s28, 0xfffc0080
	s_addc_u32 s31, s29, -1
	s_cmp_eq_u32 s56, 12
	s_cselect_b32 s39, s23, s31
	s_cselect_b32 s38, s52, s30
	s_cselect_b32 s31, s21, s55
	s_cselect_b32 s30, s53, s54
	v_lshl_add_u64 v[150:151], s[28:29], 0, v[138:139]
	s_add_i32 m0, s44, 0xc000
	ds_read_b128 v[188:191], v156
	ds_read_b128 v[192:195], v156 offset:1024
	ds_read_b128 v[196:199], v156 offset:2048
	ds_read_b128 v[200:203], v156 offset:3072
	ds_read_b128 v[204:207], v156 offset:4096
	ds_read_b128 v[212:215], v156 offset:5120
	ds_read_b128 v[216:219], v156 offset:6144
	ds_read_b128 v[220:223], v156 offset:7168
	global_load_lds_dwordx4 v[150:151], off
	v_lshl_add_u64 v[150:151], s[28:29], 0, v[140:141]
	s_add_i32 m0, s44, 0xe000
	s_nop 0
	global_load_lds_dwordx4 v[150:151], off
	s_waitcnt vmcnt(8)
	s_waitcnt lgkmcnt(0)
	s_barrier
	s_setprio 1
	s_waitcnt lgkmcnt(0)
	v_mfma_f32_16x16x32_bf16 v[118:121], v[146:149], v[188:191], 0
	v_mfma_f32_16x16x32_bf16 v[126:129], v[162:165], v[188:191], 0
	v_mfma_f32_16x16x32_bf16 v[110:113], v[146:149], v[196:199], 0
	v_mfma_f32_16x16x32_bf16 v[106:109], v[162:165], v[196:199], 0
	v_mfma_f32_16x16x32_bf16 v[86:89], v[146:149], v[204:207], 0
	v_mfma_f32_16x16x32_bf16 v[94:97], v[162:165], v[204:207], 0
	v_mfma_f32_16x16x32_bf16 v[78:81], v[146:149], v[216:219], 0
	v_mfma_f32_16x16x32_bf16 v[74:77], v[162:165], v[216:219], 0
	v_mfma_f32_16x16x32_bf16 v[118:121], v[158:161], v[192:195], v[118:121]
	v_mfma_f32_16x16x32_bf16 v[126:129], v[166:169], v[192:195], v[126:129]
	v_mfma_f32_16x16x32_bf16 v[110:113], v[158:161], v[200:203], v[110:113]
	v_mfma_f32_16x16x32_bf16 v[106:109], v[166:169], v[200:203], v[106:109]
	v_mfma_f32_16x16x32_bf16 v[86:89], v[158:161], v[212:215], v[86:89]
	v_mfma_f32_16x16x32_bf16 v[94:97], v[166:169], v[212:215], v[94:97]
	v_mfma_f32_16x16x32_bf16 v[78:81], v[158:161], v[220:223], v[78:81]
	v_mfma_f32_16x16x32_bf16 v[74:77], v[166:169], v[220:223], v[74:77]
	s_setprio 0
	s_setprio 1
	v_mfma_f32_16x16x32_bf16 v[114:117], v[172:175], v[188:191], 0
	v_mfma_f32_16x16x32_bf16 v[122:125], v[180:183], v[188:191], 0
	v_mfma_f32_16x16x32_bf16 v[102:105], v[172:175], v[196:199], 0
	v_mfma_f32_16x16x32_bf16 v[98:101], v[180:183], v[196:199], 0
	v_mfma_f32_16x16x32_bf16 v[82:85], v[172:175], v[204:207], 0
	v_mfma_f32_16x16x32_bf16 v[90:93], v[180:183], v[204:207], 0
	v_mfma_f32_16x16x32_bf16 v[70:73], v[172:175], v[216:219], 0
	v_mfma_f32_16x16x32_bf16 v[66:69], v[180:183], v[216:219], 0
	v_mfma_f32_16x16x32_bf16 v[114:117], v[176:179], v[192:195], v[114:117]
	v_mfma_f32_16x16x32_bf16 v[122:125], v[184:187], v[192:195], v[122:125]
	v_mfma_f32_16x16x32_bf16 v[102:105], v[176:179], v[200:203], v[102:105]
	v_mfma_f32_16x16x32_bf16 v[98:101], v[184:187], v[200:203], v[98:101]
	v_mfma_f32_16x16x32_bf16 v[82:85], v[176:179], v[212:215], v[82:85]
	v_mfma_f32_16x16x32_bf16 v[90:93], v[184:187], v[212:215], v[90:93]
	v_mfma_f32_16x16x32_bf16 v[70:73], v[176:179], v[220:223], v[70:73]
	v_mfma_f32_16x16x32_bf16 v[66:69], v[184:187], v[220:223], v[66:69]
	s_setprio 0
	s_barrier
	s_add_i32 s42, s36, s19
	v_lshl_add_u64 v[150:151], s[30:31], 0, v[134:135]
	s_mov_b32 m0, s42
	ds_read_b128 v[188:191], v156 offset:16384
	ds_read_b128 v[192:195], v156 offset:17408
	ds_read_b128 v[196:199], v156 offset:18432
	ds_read_b128 v[200:203], v156 offset:19456
	ds_read_b128 v[204:207], v156 offset:20480
	ds_read_b128 v[212:215], v156 offset:21504
	ds_read_b128 v[216:219], v156 offset:22528
	ds_read_b128 v[220:223], v156 offset:23552
	global_load_lds_dwordx4 v[150:151], off
	s_add_i32 m0, s42, 0x2000
	s_add_u32 s42, s30, 0x40000
	v_lshl_add_u64 v[208:209], s[30:31], 0, v[130:131]
	s_addc_u32 s43, s31, 0
	s_add_i32 s57, s37, s19
	global_load_lds_dwordx4 v[208:209], off
	v_lshl_add_u64 v[224:225], s[42:43], 0, v[134:135]
	s_mov_b32 m0, s57
	v_lshl_add_u64 v[226:227], s[38:39], 0, v[132:133]
	global_load_lds_dwordx4 v[224:225], off
	v_lshl_add_u64 v[224:225], s[42:43], 0, v[130:131]
	s_add_i32 m0, s57, 0x2000
	s_nop 0
	global_load_lds_dwordx4 v[224:225], off
	v_lshl_add_u64 v[224:225], s[38:39], 0, v[136:137]
	s_mov_b32 m0, s44
	s_nop 0
	global_load_lds_dwordx4 v[224:225], off
	s_mov_b32 m0, s45
	s_nop 0
	global_load_lds_dwordx4 v[226:227], off
	s_waitcnt vmcnt(8)
	s_waitcnt lgkmcnt(0)
	s_barrier
	s_setprio 1
	s_waitcnt lgkmcnt(0)
	v_mfma_f32_16x16x32_bf16 v[58:61], v[146:149], v[188:191], 0
	v_mfma_f32_16x16x32_bf16 v[62:65], v[162:165], v[188:191], 0
	v_mfma_f32_16x16x32_bf16 v[46:49], v[146:149], v[196:199], 0
	v_mfma_f32_16x16x32_bf16 v[42:45], v[162:165], v[196:199], 0
	v_mfma_f32_16x16x32_bf16 v[22:25], v[146:149], v[204:207], 0
	v_mfma_f32_16x16x32_bf16 v[30:33], v[162:165], v[204:207], 0
	v_mfma_f32_16x16x32_bf16 v[14:17], v[146:149], v[216:219], 0
	v_mfma_f32_16x16x32_bf16 v[10:13], v[162:165], v[216:219], 0
	v_mfma_f32_16x16x32_bf16 v[58:61], v[158:161], v[192:195], v[58:61]
	v_mfma_f32_16x16x32_bf16 v[62:65], v[166:169], v[192:195], v[62:65]
	v_mfma_f32_16x16x32_bf16 v[46:49], v[158:161], v[200:203], v[46:49]
	v_mfma_f32_16x16x32_bf16 v[42:45], v[166:169], v[200:203], v[42:45]
	v_mfma_f32_16x16x32_bf16 v[22:25], v[158:161], v[212:215], v[22:25]
	v_mfma_f32_16x16x32_bf16 v[30:33], v[166:169], v[212:215], v[30:33]
	v_mfma_f32_16x16x32_bf16 v[14:17], v[158:161], v[220:223], v[14:17]
	v_mfma_f32_16x16x32_bf16 v[10:13], v[166:169], v[220:223], v[10:13]
	s_setprio 0
	s_setprio 1
	v_mfma_f32_16x16x32_bf16 v[50:53], v[172:175], v[188:191], 0
	v_mfma_f32_16x16x32_bf16 v[54:57], v[180:183], v[188:191], 0
	v_mfma_f32_16x16x32_bf16 v[38:41], v[172:175], v[196:199], 0
	v_mfma_f32_16x16x32_bf16 v[34:37], v[180:183], v[196:199], 0
	v_mfma_f32_16x16x32_bf16 v[18:21], v[172:175], v[204:207], 0
	v_mfma_f32_16x16x32_bf16 v[26:29], v[180:183], v[204:207], 0
	v_mfma_f32_16x16x32_bf16 v[6:9], v[172:175], v[216:219], 0
	v_mfma_f32_16x16x32_bf16 v[2:5], v[180:183], v[216:219], 0
	v_mfma_f32_16x16x32_bf16 v[50:53], v[176:179], v[192:195], v[50:53]
	v_mfma_f32_16x16x32_bf16 v[54:57], v[184:187], v[192:195], v[54:57]
	v_mfma_f32_16x16x32_bf16 v[38:41], v[176:179], v[200:203], v[38:41]
	v_mfma_f32_16x16x32_bf16 v[34:37], v[184:187], v[200:203], v[34:37]
	v_mfma_f32_16x16x32_bf16 v[18:21], v[176:179], v[212:215], v[18:21]
	v_mfma_f32_16x16x32_bf16 v[26:29], v[184:187], v[212:215], v[26:29]
	v_mfma_f32_16x16x32_bf16 v[6:9], v[176:179], v[220:223], v[6:9]
	v_mfma_f32_16x16x32_bf16 v[2:5], v[184:187], v[220:223], v[2:5]
	s_setprio 0
	s_barrier
	s_add_i32 s42, 0, 0x18000
	v_add_u32_e32 v157, s42, v152
	s_add_i32 s43, 0, 0x1c000
	ds_read_b128 v[146:149], v157
	ds_read_b128 v[158:161], v157 offset:1024
	ds_read_b128 v[162:165], v157 offset:2048
	ds_read_b128 v[166:169], v157 offset:3072
	v_add_u32_e32 v157, s43, v152
	ds_read_b128 v[172:175], v157
	ds_read_b128 v[176:179], v157 offset:1024
	ds_read_b128 v[180:183], v157 offset:2048
	ds_read_b128 v[184:187], v157 offset:3072
	s_add_u32 s38, s38, 0x40000
	s_addc_u32 s39, s39, 0
	s_mov_b32 m0, s33
	v_lshl_add_u64 v[228:229], s[38:39], 0, v[136:137]
	ds_read_b128 v[188:191], v156 offset:32768
	ds_read_b128 v[192:195], v156 offset:33792
	ds_read_b128 v[196:199], v156 offset:34816
	ds_read_b128 v[200:203], v156 offset:35840
	ds_read_b128 v[204:207], v156 offset:36864
	ds_read_b128 v[212:215], v156 offset:37888
	ds_read_b128 v[216:219], v156 offset:38912
	ds_read_b128 v[220:223], v156 offset:39936
	global_load_lds_dwordx4 v[228:229], off
	v_lshl_add_u64 v[228:229], s[38:39], 0, v[132:133]
	s_mov_b32 m0, s46
	s_nop 0
	global_load_lds_dwordx4 v[228:229], off
	s_waitcnt vmcnt(8)
	s_waitcnt lgkmcnt(0)
	s_barrier
	s_setprio 1
	s_waitcnt lgkmcnt(0)
	v_mfma_f32_16x16x32_bf16 v[118:121], v[146:149], v[188:191], v[118:121]
	v_mfma_f32_16x16x32_bf16 v[126:129], v[162:165], v[188:191], v[126:129]
	v_mfma_f32_16x16x32_bf16 v[110:113], v[146:149], v[196:199], v[110:113]
	v_mfma_f32_16x16x32_bf16 v[106:109], v[162:165], v[196:199], v[106:109]
	v_mfma_f32_16x16x32_bf16 v[86:89], v[146:149], v[204:207], v[86:89]
	v_mfma_f32_16x16x32_bf16 v[94:97], v[162:165], v[204:207], v[94:97]
	v_mfma_f32_16x16x32_bf16 v[78:81], v[146:149], v[216:219], v[78:81]
	v_mfma_f32_16x16x32_bf16 v[74:77], v[162:165], v[216:219], v[74:77]
	v_mfma_f32_16x16x32_bf16 v[118:121], v[158:161], v[192:195], v[118:121]
	v_mfma_f32_16x16x32_bf16 v[126:129], v[166:169], v[192:195], v[126:129]
	v_mfma_f32_16x16x32_bf16 v[110:113], v[158:161], v[200:203], v[110:113]
	v_mfma_f32_16x16x32_bf16 v[106:109], v[166:169], v[200:203], v[106:109]
	v_mfma_f32_16x16x32_bf16 v[86:89], v[158:161], v[212:215], v[86:89]
	v_mfma_f32_16x16x32_bf16 v[94:97], v[166:169], v[212:215], v[94:97]
	v_mfma_f32_16x16x32_bf16 v[78:81], v[158:161], v[220:223], v[78:81]
	v_mfma_f32_16x16x32_bf16 v[74:77], v[166:169], v[220:223], v[74:77]
	s_setprio 0
	s_setprio 1
	v_mfma_f32_16x16x32_bf16 v[114:117], v[172:175], v[188:191], v[114:117]
	v_mfma_f32_16x16x32_bf16 v[122:125], v[180:183], v[188:191], v[122:125]
	v_mfma_f32_16x16x32_bf16 v[102:105], v[172:175], v[196:199], v[102:105]
	v_mfma_f32_16x16x32_bf16 v[98:101], v[180:183], v[196:199], v[98:101]
	v_mfma_f32_16x16x32_bf16 v[82:85], v[172:175], v[204:207], v[82:85]
	v_mfma_f32_16x16x32_bf16 v[90:93], v[180:183], v[204:207], v[90:93]
	v_mfma_f32_16x16x32_bf16 v[70:73], v[172:175], v[216:219], v[70:73]
	v_mfma_f32_16x16x32_bf16 v[66:69], v[180:183], v[216:219], v[66:69]
	v_mfma_f32_16x16x32_bf16 v[114:117], v[176:179], v[192:195], v[114:117]
	v_mfma_f32_16x16x32_bf16 v[122:125], v[184:187], v[192:195], v[122:125]
	v_mfma_f32_16x16x32_bf16 v[102:105], v[176:179], v[200:203], v[102:105]
	v_mfma_f32_16x16x32_bf16 v[98:101], v[184:187], v[200:203], v[98:101]
	v_mfma_f32_16x16x32_bf16 v[82:85], v[176:179], v[212:215], v[82:85]
	v_mfma_f32_16x16x32_bf16 v[90:93], v[184:187], v[212:215], v[90:93]
	v_mfma_f32_16x16x32_bf16 v[70:73], v[176:179], v[220:223], v[70:73]
	v_mfma_f32_16x16x32_bf16 v[66:69], v[184:187], v[220:223], v[66:69]
	s_setprio 0
	s_barrier
	s_add_i32 s38, s42, s19
	v_lshl_add_u64 v[150:151], v[150:151], 0, s[12:13]
	s_mov_b32 m0, s38
	ds_read_b128 v[188:191], v156 offset:49152
	ds_read_b128 v[192:195], v156 offset:50176
	ds_read_b128 v[196:199], v156 offset:51200
	ds_read_b128 v[200:203], v156 offset:52224
	ds_read_b128 v[204:207], v156 offset:53248
	ds_read_b128 v[212:215], v156 offset:54272
	ds_read_b128 v[216:219], v156 offset:55296
	ds_read_b128 v[220:223], v156 offset:56320
	global_load_lds_dwordx4 v[150:151], off
	s_add_i32 m0, s38, 0x2000
	s_add_u32 s30, s30, 0x40080
	v_lshl_add_u64 v[150:151], v[208:209], 0, s[12:13]
	s_addc_u32 s31, s31, 0
	s_add_i32 s38, s43, s19
	global_load_lds_dwordx4 v[150:151], off
	v_lshl_add_u64 v[150:151], s[30:31], 0, v[134:135]
	s_mov_b32 m0, s38
	s_nop 0
	global_load_lds_dwordx4 v[150:151], off
	v_lshl_add_u64 v[150:151], s[30:31], 0, v[130:131]
	s_add_i32 m0, s38, 0x2000
	s_nop 0
	global_load_lds_dwordx4 v[150:151], off
	v_lshl_add_u64 v[150:151], v[224:225], 0, s[12:13]
	s_mov_b32 m0, s48
	s_nop 0
	global_load_lds_dwordx4 v[150:151], off
	v_lshl_add_u64 v[150:151], v[226:227], 0, s[12:13]
	s_mov_b32 m0, s49
	s_nop 0
	global_load_lds_dwordx4 v[150:151], off
	s_waitcnt vmcnt(8)
	s_waitcnt lgkmcnt(0)
	s_barrier
	s_setprio 1
	s_waitcnt lgkmcnt(0)
	v_mfma_f32_16x16x32_bf16 v[58:61], v[146:149], v[188:191], v[58:61]
	v_mfma_f32_16x16x32_bf16 v[62:65], v[162:165], v[188:191], v[62:65]
	v_mfma_f32_16x16x32_bf16 v[46:49], v[146:149], v[196:199], v[46:49]
	v_mfma_f32_16x16x32_bf16 v[42:45], v[162:165], v[196:199], v[42:45]
	v_mfma_f32_16x16x32_bf16 v[22:25], v[146:149], v[204:207], v[22:25]
	v_mfma_f32_16x16x32_bf16 v[30:33], v[162:165], v[204:207], v[30:33]
	v_mfma_f32_16x16x32_bf16 v[14:17], v[146:149], v[216:219], v[14:17]
	v_mfma_f32_16x16x32_bf16 v[10:13], v[162:165], v[216:219], v[10:13]
	v_mfma_f32_16x16x32_bf16 v[58:61], v[158:161], v[192:195], v[58:61]
	v_mfma_f32_16x16x32_bf16 v[62:65], v[166:169], v[192:195], v[62:65]
	v_mfma_f32_16x16x32_bf16 v[46:49], v[158:161], v[200:203], v[46:49]
	v_mfma_f32_16x16x32_bf16 v[42:45], v[166:169], v[200:203], v[42:45]
	v_mfma_f32_16x16x32_bf16 v[22:25], v[158:161], v[212:215], v[22:25]
	v_mfma_f32_16x16x32_bf16 v[30:33], v[166:169], v[212:215], v[30:33]
	v_mfma_f32_16x16x32_bf16 v[14:17], v[158:161], v[220:223], v[14:17]
	v_mfma_f32_16x16x32_bf16 v[10:13], v[166:169], v[220:223], v[10:13]
	s_setprio 0
	s_setprio 1
	v_mfma_f32_16x16x32_bf16 v[50:53], v[172:175], v[188:191], v[50:53]
	v_mfma_f32_16x16x32_bf16 v[54:57], v[180:183], v[188:191], v[54:57]
	v_mfma_f32_16x16x32_bf16 v[38:41], v[172:175], v[196:199], v[38:41]
	v_mfma_f32_16x16x32_bf16 v[34:37], v[180:183], v[196:199], v[34:37]
	v_mfma_f32_16x16x32_bf16 v[18:21], v[172:175], v[204:207], v[18:21]
	v_mfma_f32_16x16x32_bf16 v[26:29], v[180:183], v[204:207], v[26:29]
	v_mfma_f32_16x16x32_bf16 v[6:9], v[172:175], v[216:219], v[6:9]
	v_mfma_f32_16x16x32_bf16 v[2:5], v[180:183], v[216:219], v[2:5]
	v_mfma_f32_16x16x32_bf16 v[50:53], v[176:179], v[192:195], v[50:53]
	v_mfma_f32_16x16x32_bf16 v[54:57], v[184:187], v[192:195], v[54:57]
	v_mfma_f32_16x16x32_bf16 v[38:41], v[176:179], v[200:203], v[38:41]
	v_mfma_f32_16x16x32_bf16 v[34:37], v[184:187], v[200:203], v[34:37]
	v_mfma_f32_16x16x32_bf16 v[18:21], v[176:179], v[212:215], v[18:21]
	v_mfma_f32_16x16x32_bf16 v[26:29], v[184:187], v[212:215], v[26:29]
	v_mfma_f32_16x16x32_bf16 v[6:9], v[176:179], v[220:223], v[6:9]
	v_mfma_f32_16x16x32_bf16 v[2:5], v[184:187], v[220:223], v[2:5]
	s_setprio 0
	s_barrier
	s_add_i32 s56, s56, 2
	s_add_u32 s28, s28, 0x100
	s_addc_u32 s29, s29, 0
	s_add_u32 s54, s54, 0x100
	s_addc_u32 s55, s55, 0

.LBB0_695:
	s_add_i32 s36, s33, -2
	s_add_u32 s37, s52, 0x100
	s_addc_u32 s39, s53, 0
	s_mov_b32 s47, 0
	s_waitcnt vmcnt(0)
	ds_read_b128 v[130:133], v213
	ds_read_b128 v[134:137], v213 offset:1024
	ds_read_b128 v[138:141], v213 offset:2048
	ds_read_b128 v[142:145], v213 offset:3072
	ds_read_b128 v[146:149], v214
	ds_read_b128 v[150:153], v214 offset:1024
	ds_read_b128 v[154:157], v214 offset:2048
	ds_read_b128 v[158:161], v214 offset:3072
	s_add_i32 s49, s47, 2
	s_add_u32 s52, s50, 0x100
	s_addc_u32 s53, s51, 0
	s_cmp_eq_u32 s36, s47
	s_cselect_b32 s57, s43, s53
	s_cselect_b32 s56, s42, s52
	s_cselect_b32 s55, s45, s39
	s_cselect_b32 s54, s44, s37
	v_lshl_add_u64 v[224:225], s[50:51], 0, v[174:175]
	s_add_i32 m0, s60, 0xc000
	ds_read_b128 v[180:183], v215
	ds_read_b128 v[184:187], v215 offset:1024
	ds_read_b128 v[188:191], v215 offset:2048
	ds_read_b128 v[192:195], v215 offset:3072
	ds_read_b128 v[196:199], v215 offset:4096
	ds_read_b128 v[200:203], v215 offset:5120
	ds_read_b128 v[204:207], v215 offset:6144
	ds_read_b128 v[220:223], v215 offset:7168
	global_load_lds_dwordx4 v[224:225], off
	v_lshl_add_u64 v[224:225], s[50:51], 0, v[176:177]
	s_add_i32 m0, s60, 0xe000
	s_nop 0
	global_load_lds_dwordx4 v[224:225], off
	s_waitcnt vmcnt(8)
	s_waitcnt lgkmcnt(0)
	s_barrier
	s_setprio 1
	s_waitcnt lgkmcnt(0)
	v_mfma_f32_16x16x32_bf16 v[126:129], v[130:133], v[180:183], 0
	v_mfma_f32_16x16x32_bf16 v[122:125], v[138:141], v[180:183], 0
	v_mfma_f32_16x16x32_bf16 v[118:121], v[130:133], v[188:191], 0
	v_mfma_f32_16x16x32_bf16 v[114:117], v[138:141], v[188:191], 0
	v_mfma_f32_16x16x32_bf16 v[102:105], v[130:133], v[196:199], 0
	v_mfma_f32_16x16x32_bf16 v[98:101], v[138:141], v[196:199], 0
	v_mfma_f32_16x16x32_bf16 v[86:89], v[130:133], v[204:207], 0
	v_mfma_f32_16x16x32_bf16 v[82:85], v[138:141], v[204:207], 0
	v_mfma_f32_16x16x32_bf16 v[126:129], v[134:137], v[184:187], v[126:129]
	v_mfma_f32_16x16x32_bf16 v[122:125], v[142:145], v[184:187], v[122:125]
	v_mfma_f32_16x16x32_bf16 v[118:121], v[134:137], v[192:195], v[118:121]
	v_mfma_f32_16x16x32_bf16 v[114:117], v[142:145], v[192:195], v[114:117]
	v_mfma_f32_16x16x32_bf16 v[102:105], v[134:137], v[200:203], v[102:105]
	v_mfma_f32_16x16x32_bf16 v[98:101], v[142:145], v[200:203], v[98:101]
	v_mfma_f32_16x16x32_bf16 v[86:89], v[134:137], v[220:223], v[86:89]
	v_mfma_f32_16x16x32_bf16 v[82:85], v[142:145], v[220:223], v[82:85]
	s_setprio 0
	s_setprio 1
	v_mfma_f32_16x16x32_bf16 v[110:113], v[146:149], v[180:183], 0
	v_mfma_f32_16x16x32_bf16 v[106:109], v[154:157], v[180:183], 0
	v_mfma_f32_16x16x32_bf16 v[94:97], v[146:149], v[188:191], 0
	v_mfma_f32_16x16x32_bf16 v[90:93], v[154:157], v[188:191], 0
	v_mfma_f32_16x16x32_bf16 v[78:81], v[146:149], v[196:199], 0
	v_mfma_f32_16x16x32_bf16 v[74:77], v[154:157], v[196:199], 0
	v_mfma_f32_16x16x32_bf16 v[70:73], v[146:149], v[204:207], 0
	v_mfma_f32_16x16x32_bf16 v[66:69], v[154:157], v[204:207], 0
	v_mfma_f32_16x16x32_bf16 v[110:113], v[150:153], v[184:187], v[110:113]
	v_mfma_f32_16x16x32_bf16 v[106:109], v[158:161], v[184:187], v[106:109]
	v_mfma_f32_16x16x32_bf16 v[94:97], v[150:153], v[192:195], v[94:97]
	v_mfma_f32_16x16x32_bf16 v[90:93], v[158:161], v[192:195], v[90:93]
	v_mfma_f32_16x16x32_bf16 v[78:81], v[150:153], v[200:203], v[78:81]
	v_mfma_f32_16x16x32_bf16 v[74:77], v[158:161], v[200:203], v[74:77]
	v_mfma_f32_16x16x32_bf16 v[70:73], v[150:153], v[220:223], v[70:73]
	v_mfma_f32_16x16x32_bf16 v[66:69], v[158:161], v[220:223], v[66:69]
	s_setprio 0
	s_barrier
	s_add_i32 s47, s67, s59
	v_lshl_add_u64 v[224:225], s[54:55], 0, v[164:165]
	s_mov_b32 m0, s47
	ds_read_b128 v[180:183], v215 offset:16384
	ds_read_b128 v[184:187], v215 offset:17408
	ds_read_b128 v[188:191], v215 offset:18432
	ds_read_b128 v[192:195], v215 offset:19456
	ds_read_b128 v[196:199], v215 offset:20480
	ds_read_b128 v[200:203], v215 offset:21504
	ds_read_b128 v[204:207], v215 offset:22528
	ds_read_b128 v[220:223], v215 offset:23552
	global_load_lds_dwordx4 v[224:225], off
	s_add_i32 m0, s47, 0x2000
	s_add_u32 s50, s54, 0xb0000
	v_lshl_add_u64 v[226:227], s[54:55], 0, v[168:169]
	s_addc_u32 s51, s55, 0
	s_add_i32 s47, s68, s59
	global_load_lds_dwordx4 v[226:227], off
	v_lshl_add_u64 v[228:229], s[50:51], 0, v[164:165]
	s_mov_b32 m0, s47
	v_lshl_add_u64 v[230:231], s[56:57], 0, v[166:167]
	global_load_lds_dwordx4 v[228:229], off
	v_lshl_add_u64 v[228:229], s[50:51], 0, v[168:169]
	s_add_i32 m0, s47, 0x2000
	s_nop 0
	global_load_lds_dwordx4 v[228:229], off
	v_lshl_add_u64 v[228:229], s[56:57], 0, v[162:163]
	s_mov_b32 m0, s60
	s_nop 0
	global_load_lds_dwordx4 v[228:229], off
	s_mov_b32 m0, s61
	s_nop 0
	global_load_lds_dwordx4 v[230:231], off
	s_waitcnt vmcnt(8)
	s_waitcnt lgkmcnt(0)
	s_barrier
	s_setprio 1
	s_waitcnt lgkmcnt(0)
	v_mfma_f32_16x16x32_bf16 v[62:65], v[130:133], v[180:183], 0
	v_mfma_f32_16x16x32_bf16 v[58:61], v[138:141], v[180:183], 0
	v_mfma_f32_16x16x32_bf16 v[54:57], v[130:133], v[188:191], 0
	v_mfma_f32_16x16x32_bf16 v[50:53], v[138:141], v[188:191], 0
	v_mfma_f32_16x16x32_bf16 v[38:41], v[130:133], v[196:199], 0
	v_mfma_f32_16x16x32_bf16 v[34:37], v[138:141], v[196:199], 0
	v_mfma_f32_16x16x32_bf16 v[22:25], v[130:133], v[204:207], 0
	v_mfma_f32_16x16x32_bf16 v[18:21], v[138:141], v[204:207], 0
	v_mfma_f32_16x16x32_bf16 v[62:65], v[134:137], v[184:187], v[62:65]
	v_mfma_f32_16x16x32_bf16 v[58:61], v[142:145], v[184:187], v[58:61]
	v_mfma_f32_16x16x32_bf16 v[54:57], v[134:137], v[192:195], v[54:57]
	v_mfma_f32_16x16x32_bf16 v[50:53], v[142:145], v[192:195], v[50:53]
	v_mfma_f32_16x16x32_bf16 v[38:41], v[134:137], v[200:203], v[38:41]
	v_mfma_f32_16x16x32_bf16 v[34:37], v[142:145], v[200:203], v[34:37]
	v_mfma_f32_16x16x32_bf16 v[22:25], v[134:137], v[220:223], v[22:25]
	v_mfma_f32_16x16x32_bf16 v[18:21], v[142:145], v[220:223], v[18:21]
	s_setprio 0
	s_setprio 1
	v_mfma_f32_16x16x32_bf16 v[46:49], v[146:149], v[180:183], 0
	v_mfma_f32_16x16x32_bf16 v[42:45], v[154:157], v[180:183], 0
	v_mfma_f32_16x16x32_bf16 v[30:33], v[146:149], v[188:191], 0
	v_mfma_f32_16x16x32_bf16 v[26:29], v[154:157], v[188:191], 0
	v_mfma_f32_16x16x32_bf16 v[14:17], v[146:149], v[196:199], 0
	v_mfma_f32_16x16x32_bf16 v[10:13], v[154:157], v[196:199], 0
	v_mfma_f32_16x16x32_bf16 v[6:9], v[146:149], v[204:207], 0
	v_mfma_f32_16x16x32_bf16 v[2:5], v[154:157], v[204:207], 0
	v_mfma_f32_16x16x32_bf16 v[46:49], v[150:153], v[184:187], v[46:49]
	v_mfma_f32_16x16x32_bf16 v[42:45], v[158:161], v[184:187], v[42:45]
	v_mfma_f32_16x16x32_bf16 v[30:33], v[150:153], v[192:195], v[30:33]
	v_mfma_f32_16x16x32_bf16 v[26:29], v[158:161], v[192:195], v[26:29]
	v_mfma_f32_16x16x32_bf16 v[14:17], v[150:153], v[200:203], v[14:17]
	v_mfma_f32_16x16x32_bf16 v[10:13], v[158:161], v[200:203], v[10:13]
	v_mfma_f32_16x16x32_bf16 v[6:9], v[150:153], v[220:223], v[6:9]
	v_mfma_f32_16x16x32_bf16 v[2:5], v[158:161], v[220:223], v[2:5]
	s_setprio 0
	s_barrier
	s_add_i32 s47, 0, 0x18000
	s_add_i32 s84, 0, 0x1c000
	v_add_u32_e32 v142, s47, v208
	v_add_u32_e32 v158, s84, v208
	ds_read_b128 v[130:133], v142
	ds_read_b128 v[134:137], v142 offset:1024
	ds_read_b128 v[138:141], v142 offset:2048
	ds_read_b128 v[142:145], v142 offset:3072
	ds_read_b128 v[146:149], v158
	ds_read_b128 v[150:153], v158 offset:1024
	ds_read_b128 v[154:157], v158 offset:2048
	ds_read_b128 v[158:161], v158 offset:3072
	s_add_u32 s50, s56, 0xb0000
	s_addc_u32 s51, s57, 0
	s_mov_b32 m0, s62
	v_lshl_add_u64 v[232:233], s[50:51], 0, v[162:163]
	ds_read_b128 v[180:183], v215 offset:32768
	ds_read_b128 v[184:187], v215 offset:33792
	ds_read_b128 v[188:191], v215 offset:34816
	ds_read_b128 v[192:195], v215 offset:35840
	ds_read_b128 v[196:199], v215 offset:36864
	ds_read_b128 v[200:203], v215 offset:37888
	ds_read_b128 v[204:207], v215 offset:38912
	ds_read_b128 v[220:223], v215 offset:39936
	global_load_lds_dwordx4 v[232:233], off
	v_lshl_add_u64 v[232:233], s[50:51], 0, v[166:167]
	s_mov_b32 m0, s63
	s_nop 0
	global_load_lds_dwordx4 v[232:233], off
	s_waitcnt vmcnt(8)
	s_waitcnt lgkmcnt(0)
	s_barrier
	s_setprio 1
	s_waitcnt lgkmcnt(0)
	v_mfma_f32_16x16x32_bf16 v[126:129], v[130:133], v[180:183], v[126:129]
	v_mfma_f32_16x16x32_bf16 v[122:125], v[138:141], v[180:183], v[122:125]
	v_mfma_f32_16x16x32_bf16 v[118:121], v[130:133], v[188:191], v[118:121]
	v_mfma_f32_16x16x32_bf16 v[114:117], v[138:141], v[188:191], v[114:117]
	v_mfma_f32_16x16x32_bf16 v[102:105], v[130:133], v[196:199], v[102:105]
	v_mfma_f32_16x16x32_bf16 v[98:101], v[138:141], v[196:199], v[98:101]
	v_mfma_f32_16x16x32_bf16 v[86:89], v[130:133], v[204:207], v[86:89]
	v_mfma_f32_16x16x32_bf16 v[82:85], v[138:141], v[204:207], v[82:85]
	v_mfma_f32_16x16x32_bf16 v[126:129], v[134:137], v[184:187], v[126:129]
	v_mfma_f32_16x16x32_bf16 v[122:125], v[142:145], v[184:187], v[122:125]
	v_mfma_f32_16x16x32_bf16 v[118:121], v[134:137], v[192:195], v[118:121]
	v_mfma_f32_16x16x32_bf16 v[114:117], v[142:145], v[192:195], v[114:117]
	v_mfma_f32_16x16x32_bf16 v[102:105], v[134:137], v[200:203], v[102:105]
	v_mfma_f32_16x16x32_bf16 v[98:101], v[142:145], v[200:203], v[98:101]
	v_mfma_f32_16x16x32_bf16 v[86:89], v[134:137], v[220:223], v[86:89]
	v_mfma_f32_16x16x32_bf16 v[82:85], v[142:145], v[220:223], v[82:85]
	s_setprio 0
	s_setprio 1
	v_mfma_f32_16x16x32_bf16 v[110:113], v[146:149], v[180:183], v[110:113]
	v_mfma_f32_16x16x32_bf16 v[106:109], v[154:157], v[180:183], v[106:109]
	v_mfma_f32_16x16x32_bf16 v[94:97], v[146:149], v[188:191], v[94:97]
	v_mfma_f32_16x16x32_bf16 v[90:93], v[154:157], v[188:191], v[90:93]
	v_mfma_f32_16x16x32_bf16 v[78:81], v[146:149], v[196:199], v[78:81]
	v_mfma_f32_16x16x32_bf16 v[74:77], v[154:157], v[196:199], v[74:77]
	v_mfma_f32_16x16x32_bf16 v[70:73], v[146:149], v[204:207], v[70:73]
	v_mfma_f32_16x16x32_bf16 v[66:69], v[154:157], v[204:207], v[66:69]
	v_mfma_f32_16x16x32_bf16 v[110:113], v[150:153], v[184:187], v[110:113]
	v_mfma_f32_16x16x32_bf16 v[106:109], v[158:161], v[184:187], v[106:109]
	v_mfma_f32_16x16x32_bf16 v[94:97], v[150:153], v[192:195], v[94:97]
	v_mfma_f32_16x16x32_bf16 v[90:93], v[158:161], v[192:195], v[90:93]
	v_mfma_f32_16x16x32_bf16 v[78:81], v[150:153], v[200:203], v[78:81]
	v_mfma_f32_16x16x32_bf16 v[74:77], v[158:161], v[200:203], v[74:77]
	v_mfma_f32_16x16x32_bf16 v[70:73], v[150:153], v[220:223], v[70:73]
	v_mfma_f32_16x16x32_bf16 v[66:69], v[158:161], v[220:223], v[66:69]
	s_setprio 0
	s_barrier
	s_add_i32 s47, s47, s59
	v_lshl_add_u64 v[224:225], v[224:225], 0, s[16:17]
	s_mov_b32 m0, s47
	ds_read_b128 v[180:183], v215 offset:49152
	ds_read_b128 v[184:187], v215 offset:50176
	ds_read_b128 v[188:191], v215 offset:51200
	ds_read_b128 v[192:195], v215 offset:52224
	ds_read_b128 v[196:199], v215 offset:53248
	ds_read_b128 v[200:203], v215 offset:54272
	ds_read_b128 v[204:207], v215 offset:55296
	ds_read_b128 v[220:223], v215 offset:56320
	global_load_lds_dwordx4 v[224:225], off
	s_add_i32 m0, s47, 0x2000
	s_add_u32 s50, s54, 0xb0080
	v_lshl_add_u64 v[224:225], v[226:227], 0, s[16:17]
	s_addc_u32 s51, s55, 0
	s_add_i32 s47, s84, s59
	global_load_lds_dwordx4 v[224:225], off
	v_lshl_add_u64 v[224:225], s[50:51], 0, v[164:165]
	s_mov_b32 m0, s47
	s_nop 0
	global_load_lds_dwordx4 v[224:225], off
	v_lshl_add_u64 v[224:225], s[50:51], 0, v[168:169]
	s_add_i32 m0, s47, 0x2000
	s_nop 0
	global_load_lds_dwordx4 v[224:225], off
	v_lshl_add_u64 v[224:225], v[228:229], 0, s[16:17]
	s_mov_b32 m0, s65
	s_nop 0
	global_load_lds_dwordx4 v[224:225], off
	v_lshl_add_u64 v[224:225], v[230:231], 0, s[16:17]
	s_mov_b32 m0, s66
	s_nop 0
	global_load_lds_dwordx4 v[224:225], off
	s_waitcnt vmcnt(8)
	s_waitcnt lgkmcnt(0)
	s_barrier
	s_setprio 1
	s_waitcnt lgkmcnt(0)
	v_mfma_f32_16x16x32_bf16 v[62:65], v[130:133], v[180:183], v[62:65]
	v_mfma_f32_16x16x32_bf16 v[58:61], v[138:141], v[180:183], v[58:61]
	v_mfma_f32_16x16x32_bf16 v[54:57], v[130:133], v[188:191], v[54:57]
	v_mfma_f32_16x16x32_bf16 v[50:53], v[138:141], v[188:191], v[50:53]
	v_mfma_f32_16x16x32_bf16 v[38:41], v[130:133], v[196:199], v[38:41]
	v_mfma_f32_16x16x32_bf16 v[34:37], v[138:141], v[196:199], v[34:37]
	v_mfma_f32_16x16x32_bf16 v[22:25], v[130:133], v[204:207], v[22:25]
	v_mfma_f32_16x16x32_bf16 v[18:21], v[138:141], v[204:207], v[18:21]
	v_mfma_f32_16x16x32_bf16 v[62:65], v[134:137], v[184:187], v[62:65]
	v_mfma_f32_16x16x32_bf16 v[58:61], v[142:145], v[184:187], v[58:61]
	v_mfma_f32_16x16x32_bf16 v[54:57], v[134:137], v[192:195], v[54:57]
	v_mfma_f32_16x16x32_bf16 v[50:53], v[142:145], v[192:195], v[50:53]
	v_mfma_f32_16x16x32_bf16 v[38:41], v[134:137], v[200:203], v[38:41]
	v_mfma_f32_16x16x32_bf16 v[34:37], v[142:145], v[200:203], v[34:37]
	v_mfma_f32_16x16x32_bf16 v[22:25], v[134:137], v[220:223], v[22:25]
	v_mfma_f32_16x16x32_bf16 v[18:21], v[142:145], v[220:223], v[18:21]
	s_setprio 0
	s_setprio 1
	v_mfma_f32_16x16x32_bf16 v[46:49], v[146:149], v[180:183], v[46:49]
	v_mfma_f32_16x16x32_bf16 v[42:45], v[154:157], v[180:183], v[42:45]
	v_mfma_f32_16x16x32_bf16 v[30:33], v[146:149], v[188:191], v[30:33]
	v_mfma_f32_16x16x32_bf16 v[26:29], v[154:157], v[188:191], v[26:29]
	v_mfma_f32_16x16x32_bf16 v[14:17], v[146:149], v[196:199], v[14:17]
	v_mfma_f32_16x16x32_bf16 v[10:13], v[154:157], v[196:199], v[10:13]
	v_mfma_f32_16x16x32_bf16 v[6:9], v[146:149], v[204:207], v[6:9]
	v_mfma_f32_16x16x32_bf16 v[2:5], v[154:157], v[204:207], v[2:5]
	v_mfma_f32_16x16x32_bf16 v[46:49], v[150:153], v[184:187], v[46:49]
	v_mfma_f32_16x16x32_bf16 v[42:45], v[158:161], v[184:187], v[42:45]
	v_mfma_f32_16x16x32_bf16 v[30:33], v[150:153], v[192:195], v[30:33]
	v_mfma_f32_16x16x32_bf16 v[26:29], v[158:161], v[192:195], v[26:29]
	v_mfma_f32_16x16x32_bf16 v[14:17], v[150:153], v[200:203], v[14:17]
	v_mfma_f32_16x16x32_bf16 v[10:13], v[158:161], v[200:203], v[10:13]
	v_mfma_f32_16x16x32_bf16 v[6:9], v[150:153], v[220:223], v[6:9]
	v_mfma_f32_16x16x32_bf16 v[2:5], v[158:161], v[220:223], v[2:5]
	s_setprio 0
	s_barrier
	s_add_u32 s37, s37, 0x100
	s_addc_u32 s39, s39, 0
	s_mov_b64 s[50:51], s[52:53]
	s_mov_b32 s47, s49

	.amdhsa_kernel _Z9hymba_fwd6Params
		.amdhsa_group_segment_fixed_size 0
		.amdhsa_private_segment_fixed_size 0
		.amdhsa_kernarg_size 424
		.amdhsa_user_sgpr_count 2
		.amdhsa_user_sgpr_dispatch_ptr 0
		.amdhsa_user_sgpr_queue_ptr 0
		.amdhsa_user_sgpr_kernarg_segment_ptr 1
		.amdhsa_user_sgpr_dispatch_id 0
		.amdhsa_user_sgpr_kernarg_preload_length 0
		.amdhsa_user_sgpr_kernarg_preload_offset 0
		.amdhsa_user_sgpr_private_segment_size 0
		.amdhsa_uses_dynamic_stack 0
		.amdhsa_enable_private_segment 0
		.amdhsa_system_sgpr_workgroup_id_x 1
		.amdhsa_system_sgpr_workgroup_id_y 0
		.amdhsa_system_sgpr_workgroup_id_z 0
		.amdhsa_system_sgpr_workgroup_info 0
		.amdhsa_system_vgpr_workitem_id 0
		.amdhsa_next_free_vgpr 256
		.amdhsa_next_free_sgpr 98
		.amdhsa_accum_offset 256
		.amdhsa_reserve_vcc 1
		.amdhsa_float_round_mode_32 0
		.amdhsa_float_round_mode_16_64 0
		.amdhsa_float_denorm_mode_32 3
		.amdhsa_float_denorm_mode_16_64 3
		.amdhsa_dx10_clamp 1
		.amdhsa_ieee_mode 1
		.amdhsa_fp16_overflow 0
		.amdhsa_tg_split 0
		.amdhsa_exception_fp_ieee_invalid_op 0
		.amdhsa_exception_fp_denorm_src 0
		.amdhsa_exception_fp_ieee_div_zero 0
		.amdhsa_exception_fp_ieee_overflow 0
		.amdhsa_exception_fp_ieee_underflow 0
		.amdhsa_exception_fp_ieee_inexact 0
		.amdhsa_exception_int_div_zero 0
	.end_amdhsa_kernel

amdhsa.kernels:
  - .agpr_count:     0
    .args:
      - .offset:         0
        .size:           168
        .value_kind:     by_value
      - .offset:         168
        .size:           4
        .value_kind:     hidden_block_count_x
      - .offset:         172
        .size:           4
        .value_kind:     hidden_block_count_y
      - .offset:         176
        .size:           4
        .value_kind:     hidden_block_count_z
      - .offset:         180
        .size:           2
        .value_kind:     hidden_group_size_x
      - .offset:         182
        .size:           2
        .value_kind:     hidden_group_size_y
      - .offset:         184
        .size:           2
        .value_kind:     hidden_group_size_z
      - .offset:         186
        .size:           2
        .value_kind:     hidden_remainder_x
      - .offset:         188
        .size:           2
        .value_kind:     hidden_remainder_y
      - .offset:         190
        .size:           2
        .value_kind:     hidden_remainder_z
      - .offset:         208
        .size:           8
        .value_kind:     hidden_global_offset_x
      - .offset:         216
        .size:           8
        .value_kind:     hidden_global_offset_y
      - .offset:         224
        .size:           8
        .value_kind:     hidden_global_offset_z
      - .offset:         232
        .size:           2
        .value_kind:     hidden_grid_dims
      - .offset:         288
        .size:           4
        .value_kind:     hidden_dynamic_lds_size
    .group_segment_fixed_size: 0
    .kernarg_segment_align: 8
    .kernarg_segment_size: 424
    .language:       OpenCL C
    .language_version:
      - 2
      - 0
    .max_flat_workgroup_size: 512
    .name:           _Z9hymba_fwd6Params
    .private_segment_fixed_size: 0
    .sgpr_count:     104
    .sgpr_spill_count: 27
    .symbol:         _Z9hymba_fwd6Params.kd
    .uniform_work_group_size: 1
    .uses_dynamic_stack: false
    .vgpr_count:     256
    .vgpr_spill_count: 0
    .wavefront_size: 64
